# v34 + nt cache policy on the conversion code's output stores (converted bf16 / fp8 weights are consumed phases later)
# speedup vs baseline: 1.0079x; 1.0079x over previous
; __device__ __forceinline__ unsigned cvt_pk_bf16(float lo, float hi) { unsigned r; asm volatile("v_cvt_pk_bf16_f32 %0, %1, %2" : "=v"(r) : "v"(lo), "v"(hi)); return r; }
; #define LAS __attribute__((address_space(3)))
; __device__ __forceinline__ void tr_range(const Params& p, LAS unsigned char* lds, int first, int stride, int end, int lane, int wave) {
;     ...
;         const int c = lane & 7;
; #pragma unroll
;         for (int j = 0; j < 8; ++j) { const int n = (lane >> 3) + 8 * j; const LAS float* s = scr + (8 * c) * 65 + n;
;             u32x4 o; o.x = pg8::cvt_pk_bf16(s[0 * 65], s[1 * 65]); o.y = pg8::cvt_pk_bf16(s[2 * 65], s[3 * 65]); o.z = pg8::cvt_pk_bf16(s[4 * 65], s[5 * 65]); o.w = pg8::cvt_pk_bf16(s[6 * 65], s[7 * 65]);
;             *(u32x4*)(cur.dst + (size_t)n * cur.K + 8 * c) = o; }
;         }
.LBB0_8:
	s_waitcnt lgkmcnt(0)
	ds_read2_b32 v[86:87], v22 offset1:65
	s_waitcnt lgkmcnt(0)
	v_cvt_pk_bf16_f32 v86, v86, v87
	ds_read2_b32 v[88:89], v22 offset0:130 offset1:195
	v_add_u32_e32 v19, 0x400, v22
	s_waitcnt lgkmcnt(0)
	v_cvt_pk_bf16_f32 v87, v88, v89
	ds_read2_b32 v[88:89], v19 offset0:4 offset1:69
	v_lshl_add_u64 v[92:93], s[6:7], 0, v[2:3]
	v_mov_b32_e32 v5, v3
	s_waitcnt lgkmcnt(0)
	v_cvt_pk_bf16_f32 v88, v88, v89
	ds_read2_b32 v[90:91], v19 offset0:134 offset1:199
	s_waitcnt lgkmcnt(0)
	v_cvt_pk_bf16_f32 v89, v90, v91
	v_lshl_add_u64 v[94:95], v[92:93], 0, v[4:5]
	ds_read2_b32 v[90:91], v22 offset0:8 offset1:73
	global_store_dwordx4 v[94:95], v[86:89], off nt
	v_mov_b32_e32 v7, v3
	v_lshl_add_u64 v[94:95], v[92:93], 0, v[6:7]
	s_waitcnt lgkmcnt(0)
	v_cvt_pk_bf16_f32 v86, v90, v91
	ds_read2_b32 v[88:89], v22 offset0:138 offset1:203
	s_waitcnt lgkmcnt(0)
	v_cvt_pk_bf16_f32 v87, v88, v89
	ds_read2_b32 v[88:89], v19 offset0:12 offset1:77
	s_waitcnt lgkmcnt(0)
	v_cvt_pk_bf16_f32 v88, v88, v89
	ds_read2_b32 v[90:91], v19 offset0:142 offset1:207
	s_waitcnt lgkmcnt(0)
	v_cvt_pk_bf16_f32 v89, v90, v91
	ds_read2_b32 v[90:91], v22 offset0:16 offset1:81
	global_store_dwordx4 v[94:95], v[86:89], off nt
	v_mov_b32_e32 v9, v3
	v_lshl_add_u64 v[94:95], v[92:93], 0, v[8:9]
	s_waitcnt lgkmcnt(0)
	v_cvt_pk_bf16_f32 v86, v90, v91
	ds_read2_b32 v[88:89], v22 offset0:146 offset1:211
	s_waitcnt lgkmcnt(0)
	v_cvt_pk_bf16_f32 v87, v88, v89
	ds_read2_b32 v[88:89], v19 offset0:20 offset1:85
	s_waitcnt lgkmcnt(0)
	v_cvt_pk_bf16_f32 v88, v88, v89
	ds_read2_b32 v[90:91], v19 offset0:150 offset1:215
	s_waitcnt lgkmcnt(0)
	v_cvt_pk_bf16_f32 v89, v90, v91
	ds_read2_b32 v[90:91], v22 offset0:24 offset1:89
	global_store_dwordx4 v[94:95], v[86:89], off nt
	v_mov_b32_e32 v11, v3
	v_lshl_add_u64 v[94:95], v[92:93], 0, v[10:11]
	s_waitcnt lgkmcnt(0)
	v_cvt_pk_bf16_f32 v86, v90, v91
	ds_read2_b32 v[88:89], v22 offset0:154 offset1:219
	s_waitcnt lgkmcnt(0)
	v_cvt_pk_bf16_f32 v87, v88, v89
	ds_read2_b32 v[88:89], v19 offset0:28 offset1:93
	s_waitcnt lgkmcnt(0)
	v_cvt_pk_bf16_f32 v88, v88, v89
	ds_read2_b32 v[90:91], v19 offset0:158 offset1:223
	s_waitcnt lgkmcnt(0)
	v_cvt_pk_bf16_f32 v89, v90, v91
	ds_read2_b32 v[90:91], v22 offset0:32 offset1:97
	global_store_dwordx4 v[94:95], v[86:89], off nt
	v_mov_b32_e32 v13, v3
	v_lshl_add_u64 v[94:95], v[92:93], 0, v[12:13]
	s_waitcnt lgkmcnt(0)
	v_cvt_pk_bf16_f32 v86, v90, v91
	ds_read2_b32 v[88:89], v22 offset0:162 offset1:227
	s_waitcnt lgkmcnt(0)
	v_cvt_pk_bf16_f32 v87, v88, v89
	ds_read2_b32 v[88:89], v19 offset0:36 offset1:101
	s_waitcnt lgkmcnt(0)
	v_cvt_pk_bf16_f32 v88, v88, v89
	ds_read2_b32 v[90:91], v19 offset0:166 offset1:231
	s_waitcnt lgkmcnt(0)
	v_cvt_pk_bf16_f32 v89, v90, v91
	ds_read2_b32 v[90:91], v22 offset0:40 offset1:105
	global_store_dwordx4 v[94:95], v[86:89], off nt
	v_mov_b32_e32 v15, v3
	v_lshl_add_u64 v[94:95], v[92:93], 0, v[14:15]
	s_waitcnt lgkmcnt(0)
	v_cvt_pk_bf16_f32 v86, v90, v91
	ds_read2_b32 v[88:89], v22 offset0:170 offset1:235
	s_waitcnt lgkmcnt(0)
	v_cvt_pk_bf16_f32 v87, v88, v89
	ds_read2_b32 v[88:89], v19 offset0:44 offset1:109
	s_waitcnt lgkmcnt(0)
	v_cvt_pk_bf16_f32 v88, v88, v89
	ds_read2_b32 v[90:91], v19 offset0:174 offset1:239
	s_waitcnt lgkmcnt(0)
	v_cvt_pk_bf16_f32 v89, v90, v91
	ds_read2_b32 v[90:91], v22 offset0:48 offset1:113
	global_store_dwordx4 v[94:95], v[86:89], off nt
	v_mov_b32_e32 v17, v3
	v_lshl_add_u64 v[94:95], v[92:93], 0, v[16:17]
	s_waitcnt lgkmcnt(0)
	v_cvt_pk_bf16_f32 v86, v90, v91
	ds_read2_b32 v[88:89], v22 offset0:178 offset1:243
	s_waitcnt lgkmcnt(0)
	v_cvt_pk_bf16_f32 v87, v88, v89
	ds_read2_b32 v[88:89], v19 offset0:52 offset1:117
	s_waitcnt lgkmcnt(0)
	v_cvt_pk_bf16_f32 v88, v88, v89
	ds_read2_b32 v[90:91], v19 offset0:182 offset1:247
	s_waitcnt lgkmcnt(0)
	v_cvt_pk_bf16_f32 v89, v90, v91
	ds_read2_b32 v[90:91], v22 offset0:56 offset1:121
	global_store_dwordx4 v[94:95], v[86:89], off nt
	s_add_i32 s16, s16, s17
	s_add_i32 s18, s18, s19
	s_waitcnt lgkmcnt(0)
	v_cvt_pk_bf16_f32 v86, v90, v91
	ds_read2_b32 v[88:89], v22 offset0:186 offset1:251
	s_waitcnt lgkmcnt(0)
	v_cvt_pk_bf16_f32 v87, v88, v89
	ds_read2_b32 v[88:89], v19 offset0:60 offset1:125
	s_waitcnt lgkmcnt(0)
	v_cvt_pk_bf16_f32 v88, v88, v89
	ds_read2_b32 v[90:91], v19 offset0:190 offset1:255
	v_mov_b32_e32 v19, v3
	v_lshl_add_u64 v[92:93], v[92:93], 0, v[18:19]
	s_waitcnt lgkmcnt(0)
	v_cvt_pk_bf16_f32 v89, v90, v91
	global_store_dwordx4 v[92:93], v[86:89], off nt
	s_waitcnt lgkmcnt(0)
	s_andn2_b64 vcc, exec, s[8:9]
	s_mov_b64 s[6:7], s[2:3]
	s_cbranch_vccz .LBB0_11

; __device__ __forceinline__ unsigned cvt_pk_bf16(float lo, float hi) { unsigned r; asm volatile("v_cvt_pk_bf16_f32 %0, %1, %2" : "=v"(r) : "v"(lo), "v"(hi)); return r; }
; #define LAS __attribute__((address_space(3)))
; __device__ __forceinline__ void tr_range(const Params& p, LAS unsigned char* lds, int first, int stride, int end, int lane, int wave) {
;     ...
;         const int c = lane & 7;
; #pragma unroll
;         for (int j = 0; j < 8; ++j) { const int n = (lane >> 3) + 8 * j; const LAS float* s = scr + (8 * c) * 65 + n;
;             u32x4 o; o.x = pg8::cvt_pk_bf16(s[0 * 65], s[1 * 65]); o.y = pg8::cvt_pk_bf16(s[2 * 65], s[3 * 65]); o.z = pg8::cvt_pk_bf16(s[4 * 65], s[5 * 65]); o.w = pg8::cvt_pk_bf16(s[6 * 65], s[7 * 65]);
;             *(u32x4*)(cur.dst + (size_t)n * cur.K + 8 * c) = o; }
;         }
.LBB0_264:
	ds_read2_b32 v[86:87], v11 offset1:65
	s_waitcnt lgkmcnt(0)
	v_cvt_pk_bf16_f32 v86, v86, v87
	ds_read2_b32 v[88:89], v11 offset0:130 offset1:195
	v_add_u32_e32 v85, 0x400, v11
	s_waitcnt lgkmcnt(0)
	v_cvt_pk_bf16_f32 v87, v88, v89
	ds_read2_b32 v[88:89], v85 offset0:4 offset1:69
	v_lshl_add_u64 v[92:93], s[2:3], 0, v[4:5]
	v_mad_u64_u32 v[94:95], s[2:3], s19, v6, 0
	s_waitcnt lgkmcnt(0)
	v_cvt_pk_bf16_f32 v88, v88, v89
	ds_read2_b32 v[90:91], v85 offset0:134 offset1:199
	s_waitcnt lgkmcnt(0)
	v_cvt_pk_bf16_f32 v89, v90, v91
	v_lshl_add_u64 v[94:95], v[94:95], 1, v[92:93]
	ds_read2_b32 v[90:91], v11 offset0:8 offset1:73
	global_store_dwordx4 v[94:95], v[86:89], off nt
	v_mad_u64_u32 v[94:95], s[2:3], s19, v14, 0
	s_waitcnt lgkmcnt(0)
	v_cvt_pk_bf16_f32 v86, v90, v91
	ds_read2_b32 v[88:89], v11 offset0:138 offset1:203
	s_waitcnt lgkmcnt(0)
	v_cvt_pk_bf16_f32 v87, v88, v89
	ds_read2_b32 v[88:89], v85 offset0:12 offset1:77
	s_waitcnt lgkmcnt(0)
	v_cvt_pk_bf16_f32 v88, v88, v89
	ds_read2_b32 v[90:91], v85 offset0:142 offset1:207
	s_waitcnt lgkmcnt(0)
	v_cvt_pk_bf16_f32 v89, v90, v91
	v_lshl_add_u64 v[94:95], v[94:95], 1, v[92:93]
	ds_read2_b32 v[90:91], v11 offset0:16 offset1:81
	global_store_dwordx4 v[94:95], v[86:89], off nt
	v_mad_u64_u32 v[94:95], s[2:3], s19, v16, 0
	s_waitcnt lgkmcnt(0)
	v_cvt_pk_bf16_f32 v86, v90, v91
	ds_read2_b32 v[88:89], v11 offset0:146 offset1:211
	s_waitcnt lgkmcnt(0)
	v_cvt_pk_bf16_f32 v87, v88, v89
	ds_read2_b32 v[88:89], v85 offset0:20 offset1:85
	s_waitcnt lgkmcnt(0)
	v_cvt_pk_bf16_f32 v88, v88, v89
	ds_read2_b32 v[90:91], v85 offset0:150 offset1:215
	s_waitcnt lgkmcnt(0)
	v_cvt_pk_bf16_f32 v89, v90, v91
	v_lshl_add_u64 v[94:95], v[94:95], 1, v[92:93]
	ds_read2_b32 v[90:91], v11 offset0:24 offset1:89
	global_store_dwordx4 v[94:95], v[86:89], off nt
	v_mad_u64_u32 v[94:95], s[2:3], s19, v18, 0
	s_waitcnt lgkmcnt(0)
	v_cvt_pk_bf16_f32 v86, v90, v91
	ds_read2_b32 v[88:89], v11 offset0:154 offset1:219
	s_waitcnt lgkmcnt(0)
	v_cvt_pk_bf16_f32 v87, v88, v89
	ds_read2_b32 v[88:89], v85 offset0:28 offset1:93
	s_waitcnt lgkmcnt(0)
	v_cvt_pk_bf16_f32 v88, v88, v89
	ds_read2_b32 v[90:91], v85 offset0:158 offset1:223
	s_waitcnt lgkmcnt(0)
	v_cvt_pk_bf16_f32 v89, v90, v91
	v_lshl_add_u64 v[94:95], v[94:95], 1, v[92:93]
	ds_read2_b32 v[90:91], v11 offset0:32 offset1:97
	global_store_dwordx4 v[94:95], v[86:89], off nt
	v_mad_u64_u32 v[94:95], s[2:3], s19, v20, 0
	s_waitcnt lgkmcnt(0)
	v_cvt_pk_bf16_f32 v86, v90, v91
	ds_read2_b32 v[88:89], v11 offset0:162 offset1:227
	s_waitcnt lgkmcnt(0)
	v_cvt_pk_bf16_f32 v87, v88, v89
	ds_read2_b32 v[88:89], v85 offset0:36 offset1:101
	s_waitcnt lgkmcnt(0)
	v_cvt_pk_bf16_f32 v88, v88, v89
	ds_read2_b32 v[90:91], v85 offset0:166 offset1:231
	s_waitcnt lgkmcnt(0)
	v_cvt_pk_bf16_f32 v89, v90, v91
	v_lshl_add_u64 v[94:95], v[94:95], 1, v[92:93]
	ds_read2_b32 v[90:91], v11 offset0:40 offset1:105
	global_store_dwordx4 v[94:95], v[86:89], off nt
	v_mad_u64_u32 v[94:95], s[2:3], s19, v22, 0
	s_waitcnt lgkmcnt(0)
	v_cvt_pk_bf16_f32 v86, v90, v91
	ds_read2_b32 v[88:89], v11 offset0:170 offset1:235
	s_waitcnt lgkmcnt(0)
	v_cvt_pk_bf16_f32 v87, v88, v89
	ds_read2_b32 v[88:89], v85 offset0:44 offset1:109
	s_waitcnt lgkmcnt(0)
	v_cvt_pk_bf16_f32 v88, v88, v89
	ds_read2_b32 v[90:91], v85 offset0:174 offset1:239
	s_waitcnt lgkmcnt(0)
	v_cvt_pk_bf16_f32 v89, v90, v91
	v_lshl_add_u64 v[94:95], v[94:95], 1, v[92:93]
	ds_read2_b32 v[90:91], v11 offset0:48 offset1:113
	global_store_dwordx4 v[94:95], v[86:89], off nt
	v_mad_u64_u32 v[94:95], s[2:3], s19, v24, 0
	s_waitcnt lgkmcnt(0)
	v_cvt_pk_bf16_f32 v86, v90, v91
	ds_read2_b32 v[88:89], v11 offset0:178 offset1:243
	s_waitcnt lgkmcnt(0)
	v_cvt_pk_bf16_f32 v87, v88, v89
	ds_read2_b32 v[88:89], v85 offset0:52 offset1:117
	s_waitcnt lgkmcnt(0)
	v_cvt_pk_bf16_f32 v88, v88, v89
	ds_read2_b32 v[90:91], v85 offset0:182 offset1:247
	s_waitcnt lgkmcnt(0)
	v_cvt_pk_bf16_f32 v89, v90, v91
	v_lshl_add_u64 v[94:95], v[94:95], 1, v[92:93]
	ds_read2_b32 v[90:91], v11 offset0:56 offset1:121
	global_store_dwordx4 v[94:95], v[86:89], off nt
	v_mad_u64_u32 v[94:95], s[2:3], s19, v26, 0
	s_waitcnt lgkmcnt(0)
	v_cvt_pk_bf16_f32 v86, v90, v91
	ds_read2_b32 v[88:89], v11 offset0:186 offset1:251
	s_waitcnt lgkmcnt(0)
	v_cvt_pk_bf16_f32 v87, v88, v89
	ds_read2_b32 v[88:89], v85 offset0:60 offset1:125
	s_waitcnt lgkmcnt(0)
	v_cvt_pk_bf16_f32 v88, v88, v89
	ds_read2_b32 v[90:91], v85 offset0:190 offset1:255
	s_waitcnt lgkmcnt(0)
	v_cvt_pk_bf16_f32 v89, v90, v91
	v_lshl_add_u64 v[90:91], v[94:95], 1, v[92:93]
	global_store_dwordx4 v[90:91], v[86:89], off nt

; #define LAS __attribute__((address_space(3)))
; __device__ __forceinline__ void tr_range(const Params& p, LAS unsigned char* lds, int first, int stride, int end, int lane, int wave) {
;     ...
;         if (cur.fp8) {
;             const int c = lane & 3;
; #pragma unroll
;             for (int j = 0; j < 4; ++j) { const int n = (lane >> 2) + 16 * j; const LAS float* s = scr + (16 * c) * 65 + n;
;                 u32x4 o;
;                 o.x = pk4_fp8(s[0 * 65] * W8_SCALE, s[1 * 65] * W8_SCALE, s[2 * 65] * W8_SCALE, s[3 * 65] * W8_SCALE);
;                 o.y = pk4_fp8(s[4 * 65] * W8_SCALE, s[5 * 65] * W8_SCALE, s[6 * 65] * W8_SCALE, s[7 * 65] * W8_SCALE);
;                 o.z = pk4_fp8(s[8 * 65] * W8_SCALE, s[9 * 65] * W8_SCALE, s[10 * 65] * W8_SCALE, s[11 * 65] * W8_SCALE);
;                 o.w = pk4_fp8(s[12 * 65] * W8_SCALE, s[13 * 65] * W8_SCALE, s[14 * 65] * W8_SCALE, s[15 * 65] * W8_SCALE);
;                 *(u32x4*)((unsigned char*)cur.dst + (size_t)n * cur.K + 16 * c) = o; }
.LBB0_295:
	s_waitcnt lgkmcnt(0)
	s_cmp_eq_u32 s21, 0
	s_cbranch_scc1 .LBB0_297
	ds_read2_b32 v[90:91], v9 offset1:16
	ds_read2_b32 v[92:93], v9 offset0:65 offset1:81
	ds_read2_b32 v[94:95], v9 offset0:130 offset1:146
	ds_read2_b32 v[96:97], v9 offset0:195 offset1:211
	v_add_u32_e32 v126, 0x400, v9
	s_waitcnt lgkmcnt(3)
	v_mul_f32_e32 v85, 0x44800000, v90
	s_waitcnt lgkmcnt(2)
	v_mul_f32_e32 v86, 0x44800000, v92
	v_med3_f32 v85, v85, s25, v13
	v_med3_f32 v89, v86, s25, v13
	v_mov_b32_e32 v86, 0
	v_cvt_pk_fp8_f32 v86, v85, v89
	ds_read2_b32 v[98:99], v126 offset0:4 offset1:20
	ds_read2_b32 v[100:101], v126 offset0:69 offset1:85
	ds_read2_b32 v[102:103], v126 offset0:134 offset1:150
	ds_read2_b32 v[104:105], v126 offset0:199 offset1:215
	s_waitcnt lgkmcnt(5)
	v_mul_f32_e32 v87, 0x44800000, v94
	s_waitcnt lgkmcnt(4)
	v_mul_f32_e32 v88, 0x44800000, v96
	v_med3_f32 v85, v87, s25, v13
	v_med3_f32 v87, v88, s25, v13
	v_cvt_pk_fp8_f32 v86, v85, v87 op_sel:[0,0,1]
	s_waitcnt lgkmcnt(3)
	v_mul_f32_e32 v85, 0x44800000, v98
	s_waitcnt lgkmcnt(2)
	v_mul_f32_e32 v87, 0x44800000, v100
	v_med3_f32 v85, v85, s25, v13
	v_med3_f32 v90, v87, s25, v13
	v_mov_b32_e32 v87, 0
	v_cvt_pk_fp8_f32 v87, v85, v90
	v_add_u32_e32 v127, 0x800, v9
	ds_read2_b32 v[106:107], v127 offset0:8 offset1:24
	ds_read2_b32 v[108:109], v127 offset0:73 offset1:89
	ds_read2_b32 v[110:111], v127 offset0:138 offset1:154
	ds_read2_b32 v[112:113], v127 offset0:203 offset1:219
	s_waitcnt lgkmcnt(5)
	v_mul_f32_e32 v88, 0x44800000, v102
	s_waitcnt lgkmcnt(4)
	v_mul_f32_e32 v89, 0x44800000, v104
	v_med3_f32 v85, v88, s25, v13
	v_med3_f32 v88, v89, s25, v13
	v_cvt_pk_fp8_f32 v87, v85, v88 op_sel:[0,0,1]
	s_waitcnt lgkmcnt(3)
	v_mul_f32_e32 v85, 0x44800000, v106
	s_waitcnt lgkmcnt(2)
	v_mul_f32_e32 v88, 0x44800000, v108
	v_med3_f32 v85, v85, s25, v13
	v_med3_f32 v92, v88, s25, v13
	v_mov_b32_e32 v88, 0
	v_add_u32_e32 v128, 0xc00, v9
	v_cvt_pk_fp8_f32 v88, v85, v92
	ds_read2_b32 v[114:115], v128 offset0:12 offset1:28
	ds_read2_b32 v[116:117], v128 offset0:77 offset1:93
	ds_read2_b32 v[118:119], v128 offset0:142 offset1:158
	s_waitcnt lgkmcnt(4)
	v_mul_f32_e32 v89, 0x44800000, v110
	s_waitcnt lgkmcnt(3)
	v_mul_f32_e32 v90, 0x44800000, v112
	v_med3_f32 v85, v89, s25, v13
	v_med3_f32 v89, v90, s25, v13
	ds_read2_b32 v[120:121], v128 offset0:207 offset1:223
	v_cvt_pk_fp8_f32 v88, v85, v89 op_sel:[0,0,1]
	s_waitcnt lgkmcnt(3)
	v_mul_f32_e32 v85, 0x44800000, v114
	s_waitcnt lgkmcnt(2)
	v_mul_f32_e32 v89, 0x44800000, v116
	v_med3_f32 v85, v85, s25, v13
	v_med3_f32 v92, v89, s25, v13
	v_mov_b32_e32 v89, 0
	v_cvt_pk_fp8_f32 v89, v85, v92
	s_waitcnt lgkmcnt(1)
	v_mul_f32_e32 v90, 0x44800000, v118
	s_waitcnt lgkmcnt(0)
	v_mul_f32_e32 v85, 0x44800000, v120
	v_med3_f32 v90, v90, s25, v13
	v_med3_f32 v85, v85, s25, v13
	v_cvt_pk_fp8_f32 v89, v90, v85 op_sel:[0,0,1]
	v_lshl_add_u64 v[122:123], s[2:3], 0, v[130:131]
	v_mad_u64_u32 v[124:125], s[10:11], s19, v2, v[122:123]
	global_store_dwordx4 v[124:125], v[86:89], off nt
	v_mul_f32_e32 v85, 0x44800000, v91
	v_med3_f32 v85, v85, s25, v13
	v_mul_f32_e32 v86, 0x44800000, v93
	v_med3_f32 v88, v86, s25, v13
	v_mov_b32_e32 v86, 0
	v_cvt_pk_fp8_f32 v86, v85, v88
	v_mul_f32_e32 v87, 0x44800000, v95
	v_mul_f32_e32 v85, 0x44800000, v97
	v_med3_f32 v87, v87, s25, v13
	v_med3_f32 v85, v85, s25, v13
	v_cvt_pk_fp8_f32 v86, v87, v85 op_sel:[0,0,1]
	v_mul_f32_e32 v85, 0x44800000, v99
	v_mul_f32_e32 v87, 0x44800000, v101
	v_med3_f32 v85, v85, s25, v13
	v_med3_f32 v89, v87, s25, v13
	v_mov_b32_e32 v87, 0
	v_cvt_pk_fp8_f32 v87, v85, v89
	v_mul_f32_e32 v88, 0x44800000, v103
	v_mul_f32_e32 v85, 0x44800000, v105
	v_med3_f32 v88, v88, s25, v13
	v_med3_f32 v85, v85, s25, v13
	v_cvt_pk_fp8_f32 v87, v88, v85 op_sel:[0,0,1]
	v_mul_f32_e32 v85, 0x44800000, v107
	v_mul_f32_e32 v88, 0x44800000, v109
	v_med3_f32 v85, v85, s25, v13
	v_med3_f32 v90, v88, s25, v13
	v_mov_b32_e32 v88, 0
	v_cvt_pk_fp8_f32 v88, v85, v90
	v_mul_f32_e32 v89, 0x44800000, v111
	v_mul_f32_e32 v85, 0x44800000, v113
	v_med3_f32 v89, v89, s25, v13
	v_med3_f32 v85, v85, s25, v13
	v_cvt_pk_fp8_f32 v88, v89, v85 op_sel:[0,0,1]
	v_mul_f32_e32 v85, 0x44800000, v115
	v_mul_f32_e32 v89, 0x44800000, v117
	v_med3_f32 v85, v85, s25, v13
	v_med3_f32 v91, v89, s25, v13
	v_mov_b32_e32 v89, 0
	v_cvt_pk_fp8_f32 v89, v85, v91
	v_mul_f32_e32 v90, 0x44800000, v119
	v_mul_f32_e32 v85, 0x44800000, v121
	v_med3_f32 v90, v90, s25, v13
	v_med3_f32 v85, v85, s25, v13
	v_cvt_pk_fp8_f32 v89, v90, v85 op_sel:[0,0,1]
	ds_read2_b32 v[92:93], v9 offset0:32 offset1:48
	ds_read2_b32 v[94:95], v9 offset0:97 offset1:113
	ds_read2_b32 v[96:97], v9 offset0:162 offset1:178
	ds_read2_b32 v[98:99], v9 offset0:227 offset1:243
	v_mad_u64_u32 v[90:91], s[10:11], s19, v8, v[122:123]
	global_store_dwordx4 v[90:91], v[86:89], off nt
	s_waitcnt lgkmcnt(3)
; #define LAS __attribute__((address_space(3)))
; __device__ __forceinline__ void tr_range(const Params& p, LAS unsigned char* lds, int first, int stride, int end, int lane, int wave) {
;     ...
;         if (cur.fp8) {
;             const int c = lane & 3;
; #pragma unroll
;             for (int j = 0; j < 4; ++j) { const int n = (lane >> 2) + 16 * j; const LAS float* s = scr + (16 * c) * 65 + n;
;                 u32x4 o;
;                 o.x = pk4_fp8(s[0 * 65] * W8_SCALE, s[1 * 65] * W8_SCALE, s[2 * 65] * W8_SCALE, s[3 * 65] * W8_SCALE);
;                 o.y = pk4_fp8(s[4 * 65] * W8_SCALE, s[5 * 65] * W8_SCALE, s[6 * 65] * W8_SCALE, s[7 * 65] * W8_SCALE);
;                 o.z = pk4_fp8(s[8 * 65] * W8_SCALE, s[9 * 65] * W8_SCALE, s[10 * 65] * W8_SCALE, s[11 * 65] * W8_SCALE);
;                 o.w = pk4_fp8(s[12 * 65] * W8_SCALE, s[13 * 65] * W8_SCALE, s[14 * 65] * W8_SCALE, s[15 * 65] * W8_SCALE);
;                 *(u32x4*)((unsigned char*)cur.dst + (size_t)n * cur.K + 16 * c) = o; }
	v_mul_f32_e32 v85, 0x44800000, v92
	v_med3_f32 v85, v85, s25, v13
	s_waitcnt lgkmcnt(2)
	v_mul_f32_e32 v86, 0x44800000, v94
	v_med3_f32 v89, v86, s25, v13
	v_mov_b32_e32 v86, 0
	v_cvt_pk_fp8_f32 v86, v85, v89
	ds_read2_b32 v[90:91], v126 offset0:36 offset1:52
	ds_read2_b32 v[100:101], v126 offset0:101 offset1:117
	ds_read2_b32 v[102:103], v126 offset0:166 offset1:182
	ds_read2_b32 v[104:105], v126 offset0:231 offset1:247
	s_waitcnt lgkmcnt(5)
	v_mul_f32_e32 v87, 0x44800000, v96
	s_waitcnt lgkmcnt(4)
	v_mul_f32_e32 v88, 0x44800000, v98
	v_med3_f32 v85, v87, s25, v13
	v_med3_f32 v87, v88, s25, v13
	v_cvt_pk_fp8_f32 v86, v85, v87 op_sel:[0,0,1]
	s_waitcnt lgkmcnt(3)
	v_mul_f32_e32 v85, 0x44800000, v90
	s_waitcnt lgkmcnt(2)
	v_mul_f32_e32 v87, 0x44800000, v100
	v_med3_f32 v85, v85, s25, v13
	v_med3_f32 v90, v87, s25, v13
	v_mov_b32_e32 v87, 0
	v_cvt_pk_fp8_f32 v87, v85, v90
	ds_read2_b32 v[106:107], v127 offset0:40 offset1:56
	ds_read2_b32 v[108:109], v127 offset0:105 offset1:121
	ds_read2_b32 v[110:111], v127 offset0:170 offset1:186
	ds_read2_b32 v[112:113], v127 offset0:235 offset1:251
	s_waitcnt lgkmcnt(5)
	v_mul_f32_e32 v88, 0x44800000, v102
	s_waitcnt lgkmcnt(4)
	v_mul_f32_e32 v89, 0x44800000, v104
	v_med3_f32 v85, v88, s25, v13
	v_med3_f32 v88, v89, s25, v13
	v_cvt_pk_fp8_f32 v87, v85, v88 op_sel:[0,0,1]
	s_waitcnt lgkmcnt(3)
	v_mul_f32_e32 v85, 0x44800000, v106
	s_waitcnt lgkmcnt(2)
	v_mul_f32_e32 v88, 0x44800000, v108
	v_med3_f32 v85, v85, s25, v13
	v_med3_f32 v92, v88, s25, v13
	v_mov_b32_e32 v88, 0
	v_cvt_pk_fp8_f32 v88, v85, v92
	ds_read2_b32 v[114:115], v128 offset0:44 offset1:60
	ds_read2_b32 v[116:117], v128 offset0:109 offset1:125
	ds_read2_b32 v[118:119], v128 offset0:174 offset1:190
	s_waitcnt lgkmcnt(4)
	v_mul_f32_e32 v89, 0x44800000, v110
	s_waitcnt lgkmcnt(3)
	v_mul_f32_e32 v90, 0x44800000, v112
	v_med3_f32 v85, v89, s25, v13
	v_med3_f32 v89, v90, s25, v13
	ds_read2_b32 v[120:121], v128 offset0:239 offset1:255
	v_cvt_pk_fp8_f32 v88, v85, v89 op_sel:[0,0,1]
	s_waitcnt lgkmcnt(3)
	v_mul_f32_e32 v85, 0x44800000, v114
	s_waitcnt lgkmcnt(2)
	v_mul_f32_e32 v89, 0x44800000, v116
	v_med3_f32 v85, v85, s25, v13
	v_med3_f32 v92, v89, s25, v13
	v_mov_b32_e32 v89, 0
	v_cvt_pk_fp8_f32 v89, v85, v92
	s_waitcnt lgkmcnt(1)
	v_mul_f32_e32 v90, 0x44800000, v118
	s_waitcnt lgkmcnt(0)
	v_mul_f32_e32 v85, 0x44800000, v120
	v_med3_f32 v90, v90, s25, v13
	v_med3_f32 v85, v85, s25, v13
	v_cvt_pk_fp8_f32 v89, v90, v85 op_sel:[0,0,1]
	v_mul_f32_e32 v85, 0x44800000, v93
	v_mul_f32_e32 v90, 0x44800000, v95
	v_med3_f32 v85, v85, s25, v13
	v_med3_f32 v93, v90, s25, v13
	v_mov_b32_e32 v90, 0
	v_cvt_pk_fp8_f32 v90, v85, v93
	v_mul_f32_e32 v92, 0x44800000, v97
	v_mul_f32_e32 v85, 0x44800000, v99
	v_med3_f32 v92, v92, s25, v13
	v_med3_f32 v85, v85, s25, v13
	v_cvt_pk_fp8_f32 v90, v92, v85 op_sel:[0,0,1]
	v_mul_f32_e32 v85, 0x44800000, v91
	v_mul_f32_e32 v91, 0x44800000, v101
	v_med3_f32 v85, v85, s25, v13
	v_med3_f32 v93, v91, s25, v13
	v_mov_b32_e32 v91, 0
	v_cvt_pk_fp8_f32 v91, v85, v93
	v_mul_f32_e32 v92, 0x44800000, v103
	v_mul_f32_e32 v85, 0x44800000, v105
	v_med3_f32 v92, v92, s25, v13
	v_med3_f32 v85, v85, s25, v13
	v_cvt_pk_fp8_f32 v91, v92, v85 op_sel:[0,0,1]
	v_mul_f32_e32 v85, 0x44800000, v107
	v_mul_f32_e32 v92, 0x44800000, v109
	v_med3_f32 v85, v85, s25, v13
	v_med3_f32 v94, v92, s25, v13
	v_mov_b32_e32 v92, 0
	v_cvt_pk_fp8_f32 v92, v85, v94
	v_mul_f32_e32 v93, 0x44800000, v111
	v_mul_f32_e32 v85, 0x44800000, v113
	v_med3_f32 v93, v93, s25, v13
	v_med3_f32 v85, v85, s25, v13
	v_cvt_pk_fp8_f32 v92, v93, v85 op_sel:[0,0,1]
	v_mul_f32_e32 v85, 0x44800000, v115
	v_mul_f32_e32 v93, 0x44800000, v117
	v_med3_f32 v85, v85, s25, v13
	v_med3_f32 v95, v93, s25, v13
	v_mov_b32_e32 v93, 0
	v_cvt_pk_fp8_f32 v93, v85, v95
	v_mul_f32_e32 v94, 0x44800000, v119
	v_mul_f32_e32 v85, 0x44800000, v121
	v_med3_f32 v94, v94, s25, v13
	v_med3_f32 v85, v85, s25, v13
	v_cvt_pk_fp8_f32 v93, v94, v85 op_sel:[0,0,1]
	v_mad_u64_u32 v[124:125], s[10:11], s19, v10, v[122:123]
	global_store_dwordx4 v[124:125], v[86:89], off nt
	s_nop 1
	v_mad_u64_u32 v[86:87], s[10:11], s19, v12, v[122:123]
	global_store_dwordx4 v[86:87], v[90:93], off nt
	s_cbranch_execnz .LBB0_265
	s_branch .LBB0_264

; __device__ __forceinline__ unsigned cvt_pk_bf16(float lo, float hi) { unsigned r; asm volatile("v_cvt_pk_bf16_f32 %0, %1, %2" : "=v"(r) : "v"(lo), "v"(hi)); return r; }
; #define LAS __attribute__((address_space(3)))
; __device__ __forceinline__ void tr_range(const Params& p, LAS unsigned char* lds, int first, int stride, int end, int lane, int wave) {
;     ...
;         const int c = lane & 7;
; #pragma unroll
;         for (int j = 0; j < 8; ++j) { const int n = (lane >> 3) + 8 * j; const LAS float* s = scr + (8 * c) * 65 + n;
;             u32x4 o; o.x = pg8::cvt_pk_bf16(s[0 * 65], s[1 * 65]); o.y = pg8::cvt_pk_bf16(s[2 * 65], s[3 * 65]); o.z = pg8::cvt_pk_bf16(s[4 * 65], s[5 * 65]); o.w = pg8::cvt_pk_bf16(s[6 * 65], s[7 * 65]);
;             *(u32x4*)(cur.dst + (size_t)n * cur.K + 8 * c) = o; }
.LBB0_1163:
	ds_read2_b32 v[86:87], v11 offset1:65
	s_waitcnt lgkmcnt(0)
	v_cvt_pk_bf16_f32 v86, v86, v87
	ds_read2_b32 v[88:89], v11 offset0:130 offset1:195
	v_add_u32_e32 v29, 0x400, v11
	s_waitcnt lgkmcnt(0)
	v_cvt_pk_bf16_f32 v87, v88, v89
	ds_read2_b32 v[88:89], v29 offset0:4 offset1:69
	v_lshl_add_u64 v[92:93], s[2:3], 0, v[4:5]
	v_mad_u64_u32 v[94:95], s[2:3], s42, v6, 0
	s_waitcnt lgkmcnt(0)
	v_cvt_pk_bf16_f32 v88, v88, v89
	ds_read2_b32 v[90:91], v29 offset0:134 offset1:199
	s_waitcnt lgkmcnt(0)
	v_cvt_pk_bf16_f32 v89, v90, v91
	v_lshl_add_u64 v[94:95], v[94:95], 1, v[92:93]
	ds_read2_b32 v[90:91], v11 offset0:8 offset1:73
	global_store_dwordx4 v[94:95], v[86:89], off nt
	v_mad_u64_u32 v[94:95], s[2:3], s42, v14, 0
	s_waitcnt lgkmcnt(0)
	v_cvt_pk_bf16_f32 v86, v90, v91
	ds_read2_b32 v[88:89], v11 offset0:138 offset1:203
	s_waitcnt lgkmcnt(0)
	v_cvt_pk_bf16_f32 v87, v88, v89
	ds_read2_b32 v[88:89], v29 offset0:12 offset1:77
	s_waitcnt lgkmcnt(0)
	v_cvt_pk_bf16_f32 v88, v88, v89
	ds_read2_b32 v[90:91], v29 offset0:142 offset1:207
	s_waitcnt lgkmcnt(0)
	v_cvt_pk_bf16_f32 v89, v90, v91
	v_lshl_add_u64 v[94:95], v[94:95], 1, v[92:93]
	ds_read2_b32 v[90:91], v11 offset0:16 offset1:81
	global_store_dwordx4 v[94:95], v[86:89], off nt
	v_mad_u64_u32 v[94:95], s[2:3], s42, v16, 0
	s_waitcnt lgkmcnt(0)
	v_cvt_pk_bf16_f32 v86, v90, v91
	ds_read2_b32 v[88:89], v11 offset0:146 offset1:211
	s_waitcnt lgkmcnt(0)
	v_cvt_pk_bf16_f32 v87, v88, v89
	ds_read2_b32 v[88:89], v29 offset0:20 offset1:85
	s_waitcnt lgkmcnt(0)
	v_cvt_pk_bf16_f32 v88, v88, v89
	ds_read2_b32 v[90:91], v29 offset0:150 offset1:215
	s_waitcnt lgkmcnt(0)
	v_cvt_pk_bf16_f32 v89, v90, v91
	v_lshl_add_u64 v[94:95], v[94:95], 1, v[92:93]
	ds_read2_b32 v[90:91], v11 offset0:24 offset1:89
	global_store_dwordx4 v[94:95], v[86:89], off nt
	v_mad_u64_u32 v[94:95], s[2:3], s42, v18, 0
	s_waitcnt lgkmcnt(0)
	v_cvt_pk_bf16_f32 v86, v90, v91
	ds_read2_b32 v[88:89], v11 offset0:154 offset1:219
	s_waitcnt lgkmcnt(0)
	v_cvt_pk_bf16_f32 v87, v88, v89
	ds_read2_b32 v[88:89], v29 offset0:28 offset1:93
	s_waitcnt lgkmcnt(0)
	v_cvt_pk_bf16_f32 v88, v88, v89
	ds_read2_b32 v[90:91], v29 offset0:158 offset1:223
	s_waitcnt lgkmcnt(0)
	v_cvt_pk_bf16_f32 v89, v90, v91
	v_lshl_add_u64 v[94:95], v[94:95], 1, v[92:93]
	ds_read2_b32 v[90:91], v11 offset0:32 offset1:97
	global_store_dwordx4 v[94:95], v[86:89], off nt
	v_mad_u64_u32 v[94:95], s[2:3], s42, v20, 0
	s_waitcnt lgkmcnt(0)
	v_cvt_pk_bf16_f32 v86, v90, v91
	ds_read2_b32 v[88:89], v11 offset0:162 offset1:227
	s_waitcnt lgkmcnt(0)
	v_cvt_pk_bf16_f32 v87, v88, v89
	ds_read2_b32 v[88:89], v29 offset0:36 offset1:101
	s_waitcnt lgkmcnt(0)
	v_cvt_pk_bf16_f32 v88, v88, v89
	ds_read2_b32 v[90:91], v29 offset0:166 offset1:231
	s_waitcnt lgkmcnt(0)
	v_cvt_pk_bf16_f32 v89, v90, v91
	v_lshl_add_u64 v[94:95], v[94:95], 1, v[92:93]
	ds_read2_b32 v[90:91], v11 offset0:40 offset1:105
	global_store_dwordx4 v[94:95], v[86:89], off nt
	v_mad_u64_u32 v[94:95], s[2:3], s42, v22, 0
	s_waitcnt lgkmcnt(0)
	v_cvt_pk_bf16_f32 v86, v90, v91
	ds_read2_b32 v[88:89], v11 offset0:170 offset1:235
	s_waitcnt lgkmcnt(0)
	v_cvt_pk_bf16_f32 v87, v88, v89
	ds_read2_b32 v[88:89], v29 offset0:44 offset1:109
	s_waitcnt lgkmcnt(0)
	v_cvt_pk_bf16_f32 v88, v88, v89
	ds_read2_b32 v[90:91], v29 offset0:174 offset1:239
	s_waitcnt lgkmcnt(0)
	v_cvt_pk_bf16_f32 v89, v90, v91
	v_lshl_add_u64 v[94:95], v[94:95], 1, v[92:93]
	ds_read2_b32 v[90:91], v11 offset0:48 offset1:113
	global_store_dwordx4 v[94:95], v[86:89], off nt
	v_mad_u64_u32 v[94:95], s[2:3], s42, v24, 0
	s_waitcnt lgkmcnt(0)
	v_cvt_pk_bf16_f32 v86, v90, v91
	ds_read2_b32 v[88:89], v11 offset0:178 offset1:243
	s_waitcnt lgkmcnt(0)
	v_cvt_pk_bf16_f32 v87, v88, v89
	ds_read2_b32 v[88:89], v29 offset0:52 offset1:117
	s_waitcnt lgkmcnt(0)
	v_cvt_pk_bf16_f32 v88, v88, v89
	ds_read2_b32 v[90:91], v29 offset0:182 offset1:247
	s_waitcnt lgkmcnt(0)
	v_cvt_pk_bf16_f32 v89, v90, v91
	v_lshl_add_u64 v[94:95], v[94:95], 1, v[92:93]
	ds_read2_b32 v[90:91], v11 offset0:56 offset1:121
	global_store_dwordx4 v[94:95], v[86:89], off nt
	v_mad_u64_u32 v[94:95], s[2:3], s42, v26, 0
	s_waitcnt lgkmcnt(0)
	v_cvt_pk_bf16_f32 v86, v90, v91
	ds_read2_b32 v[88:89], v11 offset0:186 offset1:251
	s_waitcnt lgkmcnt(0)
	v_cvt_pk_bf16_f32 v87, v88, v89
	ds_read2_b32 v[88:89], v29 offset0:60 offset1:125
	s_waitcnt lgkmcnt(0)
	v_cvt_pk_bf16_f32 v88, v88, v89
	ds_read2_b32 v[90:91], v29 offset0:190 offset1:255
	s_waitcnt lgkmcnt(0)
	v_cvt_pk_bf16_f32 v89, v90, v91
	v_lshl_add_u64 v[90:91], v[94:95], 1, v[92:93]
	global_store_dwordx4 v[90:91], v[86:89], off nt

; #define LAS __attribute__((address_space(3)))
; __device__ __forceinline__ void tr_range(const Params& p, LAS unsigned char* lds, int first, int stride, int end, int lane, int wave) {
;     ...
;         if (cur.fp8) {
;             const int c = lane & 3;
; #pragma unroll
;             for (int j = 0; j < 4; ++j) { const int n = (lane >> 2) + 16 * j; const LAS float* s = scr + (16 * c) * 65 + n;
;                 u32x4 o;
;                 o.x = pk4_fp8(s[0 * 65] * W8_SCALE, s[1 * 65] * W8_SCALE, s[2 * 65] * W8_SCALE, s[3 * 65] * W8_SCALE);
;                 o.y = pk4_fp8(s[4 * 65] * W8_SCALE, s[5 * 65] * W8_SCALE, s[6 * 65] * W8_SCALE, s[7 * 65] * W8_SCALE);
;                 o.z = pk4_fp8(s[8 * 65] * W8_SCALE, s[9 * 65] * W8_SCALE, s[10 * 65] * W8_SCALE, s[11 * 65] * W8_SCALE);
;                 o.w = pk4_fp8(s[12 * 65] * W8_SCALE, s[13 * 65] * W8_SCALE, s[14 * 65] * W8_SCALE, s[15 * 65] * W8_SCALE);
;                 *(u32x4*)((unsigned char*)cur.dst + (size_t)n * cur.K + 16 * c) = o; }
.LBB0_1207:
	s_waitcnt lgkmcnt(0)
	s_cmp_eq_u32 s44, 0
	s_cbranch_scc1 .LBB0_1209
	ds_read2_b32 v[90:91], v9 offset1:16
	ds_read2_b32 v[92:93], v9 offset0:65 offset1:81
	ds_read2_b32 v[94:95], v9 offset0:130 offset1:146
	ds_read2_b32 v[96:97], v9 offset0:195 offset1:211
	v_add_u32_e32 v126, 0x400, v9
	s_waitcnt lgkmcnt(3)
	v_mul_f32_e32 v29, 0x44800000, v90
	s_waitcnt lgkmcnt(2)
	v_mul_f32_e32 v86, 0x44800000, v92
	v_med3_f32 v29, v29, s48, v13
	v_med3_f32 v89, v86, s48, v13
	v_mov_b32_e32 v86, 0
	v_cvt_pk_fp8_f32 v86, v29, v89
	ds_read2_b32 v[98:99], v126 offset0:4 offset1:20
	ds_read2_b32 v[100:101], v126 offset0:69 offset1:85
	ds_read2_b32 v[102:103], v126 offset0:134 offset1:150
	ds_read2_b32 v[104:105], v126 offset0:199 offset1:215
	s_waitcnt lgkmcnt(5)
	v_mul_f32_e32 v87, 0x44800000, v94
	s_waitcnt lgkmcnt(4)
	v_mul_f32_e32 v88, 0x44800000, v96
	v_med3_f32 v29, v87, s48, v13
	v_med3_f32 v87, v88, s48, v13
	v_cvt_pk_fp8_f32 v86, v29, v87 op_sel:[0,0,1]
	s_waitcnt lgkmcnt(3)
	v_mul_f32_e32 v29, 0x44800000, v98
	s_waitcnt lgkmcnt(2)
	v_mul_f32_e32 v87, 0x44800000, v100
	v_med3_f32 v29, v29, s48, v13
	v_med3_f32 v90, v87, s48, v13
	v_mov_b32_e32 v87, 0
	v_cvt_pk_fp8_f32 v87, v29, v90
	v_add_u32_e32 v127, 0x800, v9
	ds_read2_b32 v[106:107], v127 offset0:8 offset1:24
	ds_read2_b32 v[108:109], v127 offset0:73 offset1:89
	ds_read2_b32 v[110:111], v127 offset0:138 offset1:154
	ds_read2_b32 v[112:113], v127 offset0:203 offset1:219
	s_waitcnt lgkmcnt(5)
	v_mul_f32_e32 v88, 0x44800000, v102
	s_waitcnt lgkmcnt(4)
	v_mul_f32_e32 v89, 0x44800000, v104
	v_med3_f32 v29, v88, s48, v13
	v_med3_f32 v88, v89, s48, v13
	v_cvt_pk_fp8_f32 v87, v29, v88 op_sel:[0,0,1]
	s_waitcnt lgkmcnt(3)
	v_mul_f32_e32 v29, 0x44800000, v106
	s_waitcnt lgkmcnt(2)
	v_mul_f32_e32 v88, 0x44800000, v108
	v_med3_f32 v29, v29, s48, v13
	v_med3_f32 v92, v88, s48, v13
	v_mov_b32_e32 v88, 0
	v_add_u32_e32 v128, 0xc00, v9
	v_cvt_pk_fp8_f32 v88, v29, v92
	ds_read2_b32 v[114:115], v128 offset0:12 offset1:28
	ds_read2_b32 v[116:117], v128 offset0:77 offset1:93
	ds_read2_b32 v[118:119], v128 offset0:142 offset1:158
	s_waitcnt lgkmcnt(4)
	v_mul_f32_e32 v89, 0x44800000, v110
	s_waitcnt lgkmcnt(3)
	v_mul_f32_e32 v90, 0x44800000, v112
	v_med3_f32 v29, v89, s48, v13
	v_med3_f32 v89, v90, s48, v13
	ds_read2_b32 v[120:121], v128 offset0:207 offset1:223
	v_cvt_pk_fp8_f32 v88, v29, v89 op_sel:[0,0,1]
	s_waitcnt lgkmcnt(3)
	v_mul_f32_e32 v29, 0x44800000, v114
	s_waitcnt lgkmcnt(2)
	v_mul_f32_e32 v89, 0x44800000, v116
	v_med3_f32 v29, v29, s48, v13
	v_med3_f32 v92, v89, s48, v13
	v_mov_b32_e32 v89, 0
	v_cvt_pk_fp8_f32 v89, v29, v92
	s_waitcnt lgkmcnt(1)
	v_mul_f32_e32 v90, 0x44800000, v118
	s_waitcnt lgkmcnt(0)
	v_mul_f32_e32 v29, 0x44800000, v120
	v_med3_f32 v90, v90, s48, v13
	v_med3_f32 v29, v29, s48, v13
	v_cvt_pk_fp8_f32 v89, v90, v29 op_sel:[0,0,1]
	v_lshl_add_u64 v[122:123], s[2:3], 0, v[130:131]
	v_mad_u64_u32 v[124:125], s[34:35], s42, v2, v[122:123]
	global_store_dwordx4 v[124:125], v[86:89], off nt
	v_mul_f32_e32 v29, 0x44800000, v91
	v_med3_f32 v29, v29, s48, v13
	v_mul_f32_e32 v86, 0x44800000, v93
	v_med3_f32 v88, v86, s48, v13
	v_mov_b32_e32 v86, 0
	v_cvt_pk_fp8_f32 v86, v29, v88
	v_mul_f32_e32 v87, 0x44800000, v95
	v_mul_f32_e32 v29, 0x44800000, v97
	v_med3_f32 v87, v87, s48, v13
	v_med3_f32 v29, v29, s48, v13
	v_cvt_pk_fp8_f32 v86, v87, v29 op_sel:[0,0,1]
	v_mul_f32_e32 v29, 0x44800000, v99
	v_mul_f32_e32 v87, 0x44800000, v101
	v_med3_f32 v29, v29, s48, v13
	v_med3_f32 v89, v87, s48, v13
	v_mov_b32_e32 v87, 0
	v_cvt_pk_fp8_f32 v87, v29, v89
	v_mul_f32_e32 v88, 0x44800000, v103
	v_mul_f32_e32 v29, 0x44800000, v105
	v_med3_f32 v88, v88, s48, v13
	v_med3_f32 v29, v29, s48, v13
	v_cvt_pk_fp8_f32 v87, v88, v29 op_sel:[0,0,1]
	v_mul_f32_e32 v29, 0x44800000, v107
	v_mul_f32_e32 v88, 0x44800000, v109
	v_med3_f32 v29, v29, s48, v13
	v_med3_f32 v90, v88, s48, v13
	v_mov_b32_e32 v88, 0
	v_cvt_pk_fp8_f32 v88, v29, v90
	v_mul_f32_e32 v89, 0x44800000, v111
	v_mul_f32_e32 v29, 0x44800000, v113
	v_med3_f32 v89, v89, s48, v13
	v_med3_f32 v29, v29, s48, v13
	v_cvt_pk_fp8_f32 v88, v89, v29 op_sel:[0,0,1]
	v_mul_f32_e32 v29, 0x44800000, v115
	v_mul_f32_e32 v89, 0x44800000, v117
	v_med3_f32 v29, v29, s48, v13
	v_med3_f32 v91, v89, s48, v13
	v_mov_b32_e32 v89, 0
	v_cvt_pk_fp8_f32 v89, v29, v91
	v_mul_f32_e32 v90, 0x44800000, v119
	v_mul_f32_e32 v29, 0x44800000, v121
	v_med3_f32 v90, v90, s48, v13
	v_med3_f32 v29, v29, s48, v13
	v_cvt_pk_fp8_f32 v89, v90, v29 op_sel:[0,0,1]
	ds_read2_b32 v[92:93], v9 offset0:32 offset1:48
	ds_read2_b32 v[94:95], v9 offset0:97 offset1:113
	ds_read2_b32 v[96:97], v9 offset0:162 offset1:178
	ds_read2_b32 v[98:99], v9 offset0:227 offset1:243
	v_mad_u64_u32 v[90:91], s[34:35], s42, v8, v[122:123]
	global_store_dwordx4 v[90:91], v[86:89], off nt
	s_waitcnt lgkmcnt(3)
; #define LAS __attribute__((address_space(3)))
; __device__ __forceinline__ void tr_range(const Params& p, LAS unsigned char* lds, int first, int stride, int end, int lane, int wave) {
;     ...
;             for (int j = 0; j < 4; ++j) { const int n = (lane >> 2) + 16 * j; const LAS float* s = scr + (16 * c) * 65 + n;
;                 u32x4 o;
;                 o.x = pk4_fp8(s[0 * 65] * W8_SCALE, s[1 * 65] * W8_SCALE, s[2 * 65] * W8_SCALE, s[3 * 65] * W8_SCALE);
;                 o.y = pk4_fp8(s[4 * 65] * W8_SCALE, s[5 * 65] * W8_SCALE, s[6 * 65] * W8_SCALE, s[7 * 65] * W8_SCALE);
;                 o.z = pk4_fp8(s[8 * 65] * W8_SCALE, s[9 * 65] * W8_SCALE, s[10 * 65] * W8_SCALE, s[11 * 65] * W8_SCALE);
;                 o.w = pk4_fp8(s[12 * 65] * W8_SCALE, s[13 * 65] * W8_SCALE, s[14 * 65] * W8_SCALE, s[15 * 65] * W8_SCALE);
;                 *(u32x4*)((unsigned char*)cur.dst + (size_t)n * cur.K + 16 * c) = o; }
	v_mul_f32_e32 v29, 0x44800000, v92
	v_med3_f32 v29, v29, s48, v13
	s_waitcnt lgkmcnt(2)
	v_mul_f32_e32 v86, 0x44800000, v94
	v_med3_f32 v89, v86, s48, v13
	v_mov_b32_e32 v86, 0
	v_cvt_pk_fp8_f32 v86, v29, v89
	ds_read2_b32 v[90:91], v126 offset0:36 offset1:52
	ds_read2_b32 v[100:101], v126 offset0:101 offset1:117
	ds_read2_b32 v[102:103], v126 offset0:166 offset1:182
	ds_read2_b32 v[104:105], v126 offset0:231 offset1:247
	s_waitcnt lgkmcnt(5)
	v_mul_f32_e32 v87, 0x44800000, v96
	s_waitcnt lgkmcnt(4)
	v_mul_f32_e32 v88, 0x44800000, v98
	v_med3_f32 v29, v87, s48, v13
	v_med3_f32 v87, v88, s48, v13
	v_cvt_pk_fp8_f32 v86, v29, v87 op_sel:[0,0,1]
	s_waitcnt lgkmcnt(3)
	v_mul_f32_e32 v29, 0x44800000, v90
	s_waitcnt lgkmcnt(2)
	v_mul_f32_e32 v87, 0x44800000, v100
	v_med3_f32 v29, v29, s48, v13
	v_med3_f32 v90, v87, s48, v13
	v_mov_b32_e32 v87, 0
	v_cvt_pk_fp8_f32 v87, v29, v90
	ds_read2_b32 v[106:107], v127 offset0:40 offset1:56
	ds_read2_b32 v[108:109], v127 offset0:105 offset1:121
	ds_read2_b32 v[110:111], v127 offset0:170 offset1:186
	ds_read2_b32 v[112:113], v127 offset0:235 offset1:251
	s_waitcnt lgkmcnt(5)
	v_mul_f32_e32 v88, 0x44800000, v102
	s_waitcnt lgkmcnt(4)
	v_mul_f32_e32 v89, 0x44800000, v104
	v_med3_f32 v29, v88, s48, v13
	v_med3_f32 v88, v89, s48, v13
	v_cvt_pk_fp8_f32 v87, v29, v88 op_sel:[0,0,1]
	s_waitcnt lgkmcnt(3)
	v_mul_f32_e32 v29, 0x44800000, v106
	s_waitcnt lgkmcnt(2)
	v_mul_f32_e32 v88, 0x44800000, v108
	v_med3_f32 v29, v29, s48, v13
	v_med3_f32 v92, v88, s48, v13
	v_mov_b32_e32 v88, 0
	v_cvt_pk_fp8_f32 v88, v29, v92
	ds_read2_b32 v[114:115], v128 offset0:44 offset1:60
	ds_read2_b32 v[116:117], v128 offset0:109 offset1:125
	ds_read2_b32 v[118:119], v128 offset0:174 offset1:190
	s_waitcnt lgkmcnt(4)
	v_mul_f32_e32 v89, 0x44800000, v110
	s_waitcnt lgkmcnt(3)
	v_mul_f32_e32 v90, 0x44800000, v112
	v_med3_f32 v29, v89, s48, v13
	v_med3_f32 v89, v90, s48, v13
	ds_read2_b32 v[120:121], v128 offset0:239 offset1:255
	v_cvt_pk_fp8_f32 v88, v29, v89 op_sel:[0,0,1]
	s_waitcnt lgkmcnt(3)
	v_mul_f32_e32 v29, 0x44800000, v114
	s_waitcnt lgkmcnt(2)
	v_mul_f32_e32 v89, 0x44800000, v116
	v_med3_f32 v29, v29, s48, v13
	v_med3_f32 v92, v89, s48, v13
	v_mov_b32_e32 v89, 0
	v_cvt_pk_fp8_f32 v89, v29, v92
	s_waitcnt lgkmcnt(1)
	v_mul_f32_e32 v90, 0x44800000, v118
	s_waitcnt lgkmcnt(0)
	v_mul_f32_e32 v29, 0x44800000, v120
	v_med3_f32 v90, v90, s48, v13
	v_med3_f32 v29, v29, s48, v13
	v_cvt_pk_fp8_f32 v89, v90, v29 op_sel:[0,0,1]
	v_mul_f32_e32 v29, 0x44800000, v93
	v_mul_f32_e32 v90, 0x44800000, v95
	v_med3_f32 v29, v29, s48, v13
	v_med3_f32 v93, v90, s48, v13
	v_mov_b32_e32 v90, 0
	v_cvt_pk_fp8_f32 v90, v29, v93
	v_mul_f32_e32 v92, 0x44800000, v97
	v_mul_f32_e32 v29, 0x44800000, v99
	v_med3_f32 v92, v92, s48, v13
	v_med3_f32 v29, v29, s48, v13
	v_cvt_pk_fp8_f32 v90, v92, v29 op_sel:[0,0,1]
	v_mul_f32_e32 v29, 0x44800000, v91
	v_mul_f32_e32 v91, 0x44800000, v101
	v_med3_f32 v29, v29, s48, v13
	v_med3_f32 v93, v91, s48, v13
	v_mov_b32_e32 v91, 0
	v_cvt_pk_fp8_f32 v91, v29, v93
	v_mul_f32_e32 v92, 0x44800000, v103
	v_mul_f32_e32 v29, 0x44800000, v105
	v_med3_f32 v92, v92, s48, v13
	v_med3_f32 v29, v29, s48, v13
	v_cvt_pk_fp8_f32 v91, v92, v29 op_sel:[0,0,1]
	v_mul_f32_e32 v29, 0x44800000, v107
	v_mul_f32_e32 v92, 0x44800000, v109
	v_med3_f32 v29, v29, s48, v13
	v_med3_f32 v94, v92, s48, v13
	v_mov_b32_e32 v92, 0
	v_cvt_pk_fp8_f32 v92, v29, v94
	v_mul_f32_e32 v93, 0x44800000, v111
	v_mul_f32_e32 v29, 0x44800000, v113
	v_med3_f32 v93, v93, s48, v13
	v_med3_f32 v29, v29, s48, v13
	v_cvt_pk_fp8_f32 v92, v93, v29 op_sel:[0,0,1]
	v_mul_f32_e32 v29, 0x44800000, v115
	v_mul_f32_e32 v93, 0x44800000, v117
	v_med3_f32 v29, v29, s48, v13
	v_med3_f32 v95, v93, s48, v13
	v_mov_b32_e32 v93, 0
	v_cvt_pk_fp8_f32 v93, v29, v95
	v_mul_f32_e32 v94, 0x44800000, v119
	v_mul_f32_e32 v29, 0x44800000, v121
	v_med3_f32 v94, v94, s48, v13
	v_med3_f32 v29, v29, s48, v13
	v_cvt_pk_fp8_f32 v93, v94, v29 op_sel:[0,0,1]
	v_mad_u64_u32 v[124:125], s[34:35], s42, v10, v[122:123]
	global_store_dwordx4 v[124:125], v[86:89], off nt
	s_nop 1
	v_mad_u64_u32 v[86:87], s[34:35], s42, v12, v[122:123]
	global_store_dwordx4 v[86:87], v[90:93], off nt
	s_cbranch_execnz .LBB0_1164
	s_branch .LBB0_1163

; __device__ __forceinline__ unsigned cvt_pk_bf16(float lo, float hi) { unsigned r; asm volatile("v_cvt_pk_bf16_f32 %0, %1, %2" : "=v"(r) : "v"(lo), "v"(hi)); return r; }
; #define LAS __attribute__((address_space(3)))
; __device__ __forceinline__ void tr_range(const Params& p, LAS unsigned char* lds, int first, int stride, int end, int lane, int wave) {
;     ...
;         const int c = lane & 7;
; #pragma unroll
;         for (int j = 0; j < 8; ++j) { const int n = (lane >> 3) + 8 * j; const LAS float* s = scr + (8 * c) * 65 + n;
;             u32x4 o; o.x = pg8::cvt_pk_bf16(s[0 * 65], s[1 * 65]); o.y = pg8::cvt_pk_bf16(s[2 * 65], s[3 * 65]); o.z = pg8::cvt_pk_bf16(s[4 * 65], s[5 * 65]); o.w = pg8::cvt_pk_bf16(s[6 * 65], s[7 * 65]);
;             *(u32x4*)(cur.dst + (size_t)n * cur.K + 8 * c) = o; }
.LBB0_1533:
	ds_read2_b32 v[88:89], v11 offset1:65
	s_waitcnt lgkmcnt(0)
	v_cvt_pk_bf16_f32 v88, v88, v89
	ds_read2_b32 v[90:91], v11 offset0:130 offset1:195
	v_add_u32_e32 v87, 0x400, v11
	s_waitcnt lgkmcnt(0)
	v_cvt_pk_bf16_f32 v89, v90, v91
	ds_read2_b32 v[90:91], v87 offset0:4 offset1:69
	s_waitcnt lgkmcnt(0)
	v_cvt_pk_bf16_f32 v90, v90, v91
	ds_read2_b32 v[92:93], v87 offset0:134 offset1:199
	v_lshl_add_u64 v[28:29], s[2:3], 0, v[4:5]
	s_waitcnt lgkmcnt(0)
	v_cvt_pk_bf16_f32 v91, v92, v93
	v_mad_u64_u32 v[92:93], s[2:3], s74, v6, 0
	v_lshl_add_u64 v[92:93], v[92:93], 1, v[28:29]
	global_store_dwordx4 v[92:93], v[88:91], off nt
	ds_read2_b32 v[88:89], v11 offset0:8 offset1:73
	s_waitcnt lgkmcnt(0)
	v_cvt_pk_bf16_f32 v88, v88, v89
	ds_read2_b32 v[90:91], v11 offset0:138 offset1:203
	s_waitcnt lgkmcnt(0)
	v_cvt_pk_bf16_f32 v89, v90, v91
	ds_read2_b32 v[90:91], v87 offset0:12 offset1:77
	s_waitcnt lgkmcnt(0)
	v_cvt_pk_bf16_f32 v90, v90, v91
	ds_read2_b32 v[92:93], v87 offset0:142 offset1:207
	s_waitcnt lgkmcnt(0)
	v_cvt_pk_bf16_f32 v91, v92, v93
	v_mad_u64_u32 v[92:93], s[2:3], s74, v14, 0
	v_lshl_add_u64 v[92:93], v[92:93], 1, v[28:29]
	global_store_dwordx4 v[92:93], v[88:91], off nt
	ds_read2_b32 v[88:89], v11 offset0:16 offset1:81
	s_waitcnt lgkmcnt(0)
	v_cvt_pk_bf16_f32 v88, v88, v89
	ds_read2_b32 v[90:91], v11 offset0:146 offset1:211
	s_waitcnt lgkmcnt(0)
	v_cvt_pk_bf16_f32 v89, v90, v91
	ds_read2_b32 v[90:91], v87 offset0:20 offset1:85
	s_waitcnt lgkmcnt(0)
	v_cvt_pk_bf16_f32 v90, v90, v91
	ds_read2_b32 v[92:93], v87 offset0:150 offset1:215
	s_waitcnt lgkmcnt(0)
	v_cvt_pk_bf16_f32 v91, v92, v93
	v_mad_u64_u32 v[92:93], s[2:3], s74, v16, 0
	v_lshl_add_u64 v[92:93], v[92:93], 1, v[28:29]
	global_store_dwordx4 v[92:93], v[88:91], off nt
	ds_read2_b32 v[88:89], v11 offset0:24 offset1:89
	s_waitcnt lgkmcnt(0)
	v_cvt_pk_bf16_f32 v88, v88, v89
	ds_read2_b32 v[90:91], v11 offset0:154 offset1:219
	s_waitcnt lgkmcnt(0)
	v_cvt_pk_bf16_f32 v89, v90, v91
	ds_read2_b32 v[90:91], v87 offset0:28 offset1:93
	s_waitcnt lgkmcnt(0)
	v_cvt_pk_bf16_f32 v90, v90, v91
	ds_read2_b32 v[92:93], v87 offset0:158 offset1:223
	s_waitcnt lgkmcnt(0)
	v_cvt_pk_bf16_f32 v91, v92, v93
	v_mad_u64_u32 v[92:93], s[2:3], s74, v18, 0
	v_lshl_add_u64 v[92:93], v[92:93], 1, v[28:29]
	global_store_dwordx4 v[92:93], v[88:91], off nt
	ds_read2_b32 v[88:89], v11 offset0:32 offset1:97
	s_waitcnt lgkmcnt(0)
	v_cvt_pk_bf16_f32 v88, v88, v89
	ds_read2_b32 v[90:91], v11 offset0:162 offset1:227
	s_waitcnt lgkmcnt(0)
	v_cvt_pk_bf16_f32 v89, v90, v91
	ds_read2_b32 v[90:91], v87 offset0:36 offset1:101
	s_waitcnt lgkmcnt(0)
	v_cvt_pk_bf16_f32 v90, v90, v91
	ds_read2_b32 v[92:93], v87 offset0:166 offset1:231
	s_waitcnt lgkmcnt(0)
	v_cvt_pk_bf16_f32 v91, v92, v93
	v_mad_u64_u32 v[92:93], s[2:3], s74, v20, 0
	v_lshl_add_u64 v[92:93], v[92:93], 1, v[28:29]
	global_store_dwordx4 v[92:93], v[88:91], off nt
	ds_read2_b32 v[88:89], v11 offset0:40 offset1:105
	s_waitcnt lgkmcnt(0)
	v_cvt_pk_bf16_f32 v88, v88, v89
	ds_read2_b32 v[90:91], v11 offset0:170 offset1:235
	s_waitcnt lgkmcnt(0)
	v_cvt_pk_bf16_f32 v89, v90, v91
	ds_read2_b32 v[90:91], v87 offset0:44 offset1:109
	s_waitcnt lgkmcnt(0)
	v_cvt_pk_bf16_f32 v90, v90, v91
	ds_read2_b32 v[92:93], v87 offset0:174 offset1:239
	s_waitcnt lgkmcnt(0)
	v_cvt_pk_bf16_f32 v91, v92, v93
	v_mad_u64_u32 v[92:93], s[2:3], s74, v22, 0
	v_lshl_add_u64 v[92:93], v[92:93], 1, v[28:29]
	global_store_dwordx4 v[92:93], v[88:91], off nt
	ds_read2_b32 v[88:89], v11 offset0:48 offset1:113
	s_waitcnt lgkmcnt(0)
	v_cvt_pk_bf16_f32 v88, v88, v89
	ds_read2_b32 v[90:91], v11 offset0:178 offset1:243
	s_waitcnt lgkmcnt(0)
	v_cvt_pk_bf16_f32 v89, v90, v91
	ds_read2_b32 v[90:91], v87 offset0:52 offset1:117
	s_waitcnt lgkmcnt(0)
	v_cvt_pk_bf16_f32 v90, v90, v91
	ds_read2_b32 v[92:93], v87 offset0:182 offset1:247
	s_waitcnt lgkmcnt(0)
	v_cvt_pk_bf16_f32 v91, v92, v93
	v_mad_u64_u32 v[92:93], s[2:3], s74, v24, 0
	v_lshl_add_u64 v[92:93], v[92:93], 1, v[28:29]
	global_store_dwordx4 v[92:93], v[88:91], off nt
	ds_read2_b32 v[88:89], v11 offset0:56 offset1:121
	s_waitcnt lgkmcnt(0)
	v_cvt_pk_bf16_f32 v88, v88, v89
	ds_read2_b32 v[90:91], v11 offset0:186 offset1:251
	s_waitcnt lgkmcnt(0)
	v_cvt_pk_bf16_f32 v89, v90, v91
	ds_read2_b32 v[90:91], v87 offset0:60 offset1:125
	s_waitcnt lgkmcnt(0)
	v_cvt_pk_bf16_f32 v90, v90, v91
	ds_read2_b32 v[92:93], v87 offset0:190 offset1:255
	s_waitcnt lgkmcnt(0)
	v_cvt_pk_bf16_f32 v91, v92, v93
	v_mad_u64_u32 v[92:93], s[2:3], s74, v26, 0
	v_lshl_add_u64 v[28:29], v[92:93], 1, v[28:29]
	global_store_dwordx4 v[28:29], v[88:91], off nt

; #define LAS __attribute__((address_space(3)))
; __device__ __forceinline__ void tr_range(const Params& p, LAS unsigned char* lds, int first, int stride, int end, int lane, int wave) {
;     ...
;         if (cur.fp8) {
;             const int c = lane & 3;
; #pragma unroll
;             for (int j = 0; j < 4; ++j) { const int n = (lane >> 2) + 16 * j; const LAS float* s = scr + (16 * c) * 65 + n;
;                 u32x4 o;
;                 o.x = pk4_fp8(s[0 * 65] * W8_SCALE, s[1 * 65] * W8_SCALE, s[2 * 65] * W8_SCALE, s[3 * 65] * W8_SCALE);
;                 o.y = pk4_fp8(s[4 * 65] * W8_SCALE, s[5 * 65] * W8_SCALE, s[6 * 65] * W8_SCALE, s[7 * 65] * W8_SCALE);
;                 o.z = pk4_fp8(s[8 * 65] * W8_SCALE, s[9 * 65] * W8_SCALE, s[10 * 65] * W8_SCALE, s[11 * 65] * W8_SCALE);
;                 o.w = pk4_fp8(s[12 * 65] * W8_SCALE, s[13 * 65] * W8_SCALE, s[14 * 65] * W8_SCALE, s[15 * 65] * W8_SCALE);
;                 *(u32x4*)((unsigned char*)cur.dst + (size_t)n * cur.K + 16 * c) = o; }
.LBB0_1598:
	s_waitcnt lgkmcnt(0)
	s_cmp_eq_u32 s75, 0
	s_cbranch_scc1 .LBB0_1600
	ds_read2_b32 v[28:29], v9 offset1:16
	ds_read2_b32 v[92:93], v9 offset0:65 offset1:81
	ds_read2_b32 v[94:95], v9 offset0:130 offset1:146
	ds_read2_b32 v[96:97], v9 offset0:195 offset1:211
	v_mov_b32_e32 v88, 0
	s_waitcnt lgkmcnt(3)
	v_mul_f32_e32 v28, 0x44800000, v28
	s_waitcnt lgkmcnt(2)
	v_mul_f32_e32 v87, 0x44800000, v92
	v_med3_f32 v28, v28, s82, v13
	v_med3_f32 v87, v87, s82, v13
	v_cvt_pk_fp8_f32 v88, v28, v87
	v_add_u32_e32 v126, 0x400, v9
	ds_read2_b32 v[98:99], v126 offset0:4 offset1:20
	ds_read2_b32 v[100:101], v126 offset0:69 offset1:85
	ds_read2_b32 v[102:103], v126 offset0:134 offset1:150
	ds_read2_b32 v[104:105], v126 offset0:199 offset1:215
	s_waitcnt lgkmcnt(5)
	v_mul_f32_e32 v89, 0x44800000, v94
	s_waitcnt lgkmcnt(4)
	v_mul_f32_e32 v90, 0x44800000, v96
	v_med3_f32 v28, v89, s82, v13
	v_med3_f32 v87, v90, s82, v13
	v_cvt_pk_fp8_f32 v88, v28, v87 op_sel:[0,0,1]
	s_waitcnt lgkmcnt(3)
	v_mul_f32_e32 v28, 0x44800000, v98
	s_waitcnt lgkmcnt(2)
	v_mul_f32_e32 v87, 0x44800000, v100
	v_med3_f32 v28, v28, s82, v13
	v_med3_f32 v87, v87, s82, v13
	v_mov_b32_e32 v89, 0
	v_cvt_pk_fp8_f32 v89, v28, v87
	v_add_u32_e32 v127, 0x800, v9
	ds_read2_b32 v[106:107], v127 offset0:8 offset1:24
	ds_read2_b32 v[108:109], v127 offset0:73 offset1:89
	ds_read2_b32 v[110:111], v127 offset0:138 offset1:154
	ds_read2_b32 v[112:113], v127 offset0:203 offset1:219
	s_waitcnt lgkmcnt(5)
	v_mul_f32_e32 v90, 0x44800000, v102
	s_waitcnt lgkmcnt(4)
	v_mul_f32_e32 v91, 0x44800000, v104
	v_med3_f32 v28, v90, s82, v13
	v_med3_f32 v87, v91, s82, v13
	v_cvt_pk_fp8_f32 v89, v28, v87 op_sel:[0,0,1]
	s_waitcnt lgkmcnt(3)
	v_mul_f32_e32 v28, 0x44800000, v106
	s_waitcnt lgkmcnt(2)
	v_mul_f32_e32 v87, 0x44800000, v108
	v_med3_f32 v28, v28, s82, v13
	v_med3_f32 v87, v87, s82, v13
	v_mov_b32_e32 v90, 0
	v_cvt_pk_fp8_f32 v90, v28, v87
	v_add_u32_e32 v87, 0xc00, v9
	ds_read2_b32 v[114:115], v87 offset0:12 offset1:28
	ds_read2_b32 v[116:117], v87 offset0:77 offset1:93
	ds_read2_b32 v[118:119], v87 offset0:142 offset1:158
	s_waitcnt lgkmcnt(4)
	v_mul_f32_e32 v91, 0x44800000, v110
	s_waitcnt lgkmcnt(3)
	v_mul_f32_e32 v92, 0x44800000, v112
	v_med3_f32 v28, v91, s82, v13
	v_med3_f32 v91, v92, s82, v13
	ds_read2_b32 v[120:121], v87 offset0:207 offset1:223
	v_cvt_pk_fp8_f32 v90, v28, v91 op_sel:[0,0,1]
	s_waitcnt lgkmcnt(3)
	v_mul_f32_e32 v28, 0x44800000, v114
	s_waitcnt lgkmcnt(2)
	v_mul_f32_e32 v91, 0x44800000, v116
	v_med3_f32 v28, v28, s82, v13
	v_med3_f32 v94, v91, s82, v13
	v_mov_b32_e32 v91, 0
	v_cvt_pk_fp8_f32 v91, v28, v94
	s_waitcnt lgkmcnt(1)
	v_mul_f32_e32 v92, 0x44800000, v118
	s_waitcnt lgkmcnt(0)
	v_mul_f32_e32 v28, 0x44800000, v120
	v_med3_f32 v92, v92, s82, v13
	v_med3_f32 v28, v28, s82, v13
	v_cvt_pk_fp8_f32 v91, v92, v28 op_sel:[0,0,1]
	v_lshl_add_u64 v[122:123], s[2:3], 0, v[130:131]
	v_mad_u64_u32 v[124:125], s[48:49], s74, v2, v[122:123]
	v_mul_f32_e32 v28, 0x44800000, v29
	v_mul_f32_e32 v29, 0x44800000, v93
	global_store_dwordx4 v[124:125], v[88:91], off nt
	v_med3_f32 v28, v28, s82, v13
	v_med3_f32 v29, v29, s82, v13
	v_mov_b32_e32 v88, 0
	v_cvt_pk_fp8_f32 v88, v28, v29
	v_mul_f32_e32 v89, 0x44800000, v95
	v_mul_f32_e32 v28, 0x44800000, v97
	v_med3_f32 v29, v89, s82, v13
	v_med3_f32 v28, v28, s82, v13
	v_cvt_pk_fp8_f32 v88, v29, v28 op_sel:[0,0,1]
	v_mul_f32_e32 v28, 0x44800000, v99
	v_mul_f32_e32 v29, 0x44800000, v101
	v_med3_f32 v28, v28, s82, v13
	v_med3_f32 v29, v29, s82, v13
	v_mov_b32_e32 v89, 0
	v_cvt_pk_fp8_f32 v89, v28, v29
	v_mul_f32_e32 v90, 0x44800000, v103
	v_mul_f32_e32 v28, 0x44800000, v105
	v_med3_f32 v29, v90, s82, v13
	v_med3_f32 v28, v28, s82, v13
	v_cvt_pk_fp8_f32 v89, v29, v28 op_sel:[0,0,1]
	v_mul_f32_e32 v28, 0x44800000, v107
	v_mul_f32_e32 v29, 0x44800000, v109
	v_med3_f32 v28, v28, s82, v13
	v_med3_f32 v29, v29, s82, v13
	v_mov_b32_e32 v90, 0
	v_cvt_pk_fp8_f32 v90, v28, v29
	v_mul_f32_e32 v91, 0x44800000, v111
	v_mul_f32_e32 v28, 0x44800000, v113
	v_med3_f32 v29, v91, s82, v13
	v_med3_f32 v28, v28, s82, v13
	v_cvt_pk_fp8_f32 v90, v29, v28 op_sel:[0,0,1]
	v_mul_f32_e32 v28, 0x44800000, v115
	v_mul_f32_e32 v29, 0x44800000, v117
	v_med3_f32 v28, v28, s82, v13
	v_med3_f32 v29, v29, s82, v13
	v_mov_b32_e32 v91, 0
	v_cvt_pk_fp8_f32 v91, v28, v29
	v_mul_f32_e32 v92, 0x44800000, v119
	v_mul_f32_e32 v28, 0x44800000, v121
	v_med3_f32 v29, v92, s82, v13
	v_med3_f32 v28, v28, s82, v13
	v_cvt_pk_fp8_f32 v91, v29, v28 op_sel:[0,0,1]
	ds_read2_b32 v[92:93], v9 offset0:32 offset1:48
	ds_read2_b32 v[94:95], v9 offset0:97 offset1:113
	ds_read2_b32 v[96:97], v9 offset0:162 offset1:178
	ds_read2_b32 v[98:99], v9 offset0:227 offset1:243
	v_mad_u64_u32 v[28:29], s[48:49], s74, v8, v[122:123]
	global_store_dwordx4 v[28:29], v[88:91], off nt
	s_waitcnt lgkmcnt(3)
; #define LAS __attribute__((address_space(3)))
; __device__ __forceinline__ void tr_range(const Params& p, LAS unsigned char* lds, int first, int stride, int end, int lane, int wave) {
;     ...
;             for (int j = 0; j < 4; ++j) { const int n = (lane >> 2) + 16 * j; const LAS float* s = scr + (16 * c) * 65 + n;
;                 u32x4 o;
;                 o.x = pk4_fp8(s[0 * 65] * W8_SCALE, s[1 * 65] * W8_SCALE, s[2 * 65] * W8_SCALE, s[3 * 65] * W8_SCALE);
;                 o.y = pk4_fp8(s[4 * 65] * W8_SCALE, s[5 * 65] * W8_SCALE, s[6 * 65] * W8_SCALE, s[7 * 65] * W8_SCALE);
;                 o.z = pk4_fp8(s[8 * 65] * W8_SCALE, s[9 * 65] * W8_SCALE, s[10 * 65] * W8_SCALE, s[11 * 65] * W8_SCALE);
;                 o.w = pk4_fp8(s[12 * 65] * W8_SCALE, s[13 * 65] * W8_SCALE, s[14 * 65] * W8_SCALE, s[15 * 65] * W8_SCALE);
;                 *(u32x4*)((unsigned char*)cur.dst + (size_t)n * cur.K + 16 * c) = o; }
	v_mul_f32_e32 v28, 0x44800000, v92
	s_waitcnt lgkmcnt(2)
	v_mul_f32_e32 v29, 0x44800000, v94
	v_med3_f32 v28, v28, s82, v13
	v_med3_f32 v29, v29, s82, v13
	v_mov_b32_e32 v88, 0
	v_cvt_pk_fp8_f32 v88, v28, v29
	ds_read2_b32 v[28:29], v126 offset0:36 offset1:52
	ds_read2_b32 v[100:101], v126 offset0:101 offset1:117
	ds_read2_b32 v[102:103], v126 offset0:166 offset1:182
	ds_read2_b32 v[104:105], v126 offset0:231 offset1:247
	s_waitcnt lgkmcnt(5)
	v_mul_f32_e32 v89, 0x44800000, v96
	s_waitcnt lgkmcnt(4)
	v_mul_f32_e32 v90, 0x44800000, v98
	v_med3_f32 v89, v89, s82, v13
	v_med3_f32 v90, v90, s82, v13
	v_cvt_pk_fp8_f32 v88, v89, v90 op_sel:[0,0,1]
	s_waitcnt lgkmcnt(3)
	v_mul_f32_e32 v28, 0x44800000, v28
	s_waitcnt lgkmcnt(2)
	v_mul_f32_e32 v89, 0x44800000, v100
	v_med3_f32 v28, v28, s82, v13
	v_med3_f32 v92, v89, s82, v13
	v_mov_b32_e32 v89, 0
	v_cvt_pk_fp8_f32 v89, v28, v92
	ds_read2_b32 v[106:107], v127 offset0:40 offset1:56
	ds_read2_b32 v[108:109], v127 offset0:105 offset1:121
	ds_read2_b32 v[110:111], v127 offset0:170 offset1:186
	ds_read2_b32 v[112:113], v127 offset0:235 offset1:251
	s_waitcnt lgkmcnt(5)
	v_mul_f32_e32 v90, 0x44800000, v102
	s_waitcnt lgkmcnt(4)
	v_mul_f32_e32 v91, 0x44800000, v104
	v_med3_f32 v28, v90, s82, v13
	v_med3_f32 v90, v91, s82, v13
	v_cvt_pk_fp8_f32 v89, v28, v90 op_sel:[0,0,1]
	s_waitcnt lgkmcnt(3)
	v_mul_f32_e32 v28, 0x44800000, v106
	s_waitcnt lgkmcnt(2)
	v_mul_f32_e32 v90, 0x44800000, v108
	v_med3_f32 v28, v28, s82, v13
	v_med3_f32 v94, v90, s82, v13
	v_mov_b32_e32 v90, 0
	v_cvt_pk_fp8_f32 v90, v28, v94
	ds_read2_b32 v[114:115], v87 offset0:44 offset1:60
	ds_read2_b32 v[116:117], v87 offset0:109 offset1:125
	ds_read2_b32 v[118:119], v87 offset0:174 offset1:190
	s_waitcnt lgkmcnt(4)
	v_mul_f32_e32 v91, 0x44800000, v110
	s_waitcnt lgkmcnt(3)
	v_mul_f32_e32 v92, 0x44800000, v112
	v_med3_f32 v28, v91, s82, v13
	v_med3_f32 v91, v92, s82, v13
	ds_read2_b32 v[120:121], v87 offset0:239 offset1:255
	v_cvt_pk_fp8_f32 v90, v28, v91 op_sel:[0,0,1]
	s_waitcnt lgkmcnt(3)
	v_mul_f32_e32 v28, 0x44800000, v114
	s_waitcnt lgkmcnt(2)
	v_mul_f32_e32 v91, 0x44800000, v116
	v_med3_f32 v28, v28, s82, v13
	v_med3_f32 v87, v91, s82, v13
	v_mov_b32_e32 v91, 0
	v_cvt_pk_fp8_f32 v91, v28, v87
	s_waitcnt lgkmcnt(1)
	v_mul_f32_e32 v92, 0x44800000, v118
	s_waitcnt lgkmcnt(0)
	v_mul_f32_e32 v28, 0x44800000, v120
	v_med3_f32 v87, v92, s82, v13
	v_med3_f32 v28, v28, s82, v13
	v_cvt_pk_fp8_f32 v91, v87, v28 op_sel:[0,0,1]
	v_mul_f32_e32 v28, 0x44800000, v93
	v_mul_f32_e32 v87, 0x44800000, v95
	v_med3_f32 v28, v28, s82, v13
	v_med3_f32 v87, v87, s82, v13
	v_mov_b32_e32 v92, 0
	v_cvt_pk_fp8_f32 v92, v28, v87
	v_mul_f32_e32 v93, 0x44800000, v97
	v_mul_f32_e32 v28, 0x44800000, v99
	v_med3_f32 v87, v93, s82, v13
	v_med3_f32 v28, v28, s82, v13
	v_cvt_pk_fp8_f32 v92, v87, v28 op_sel:[0,0,1]
	v_mul_f32_e32 v28, 0x44800000, v29
	v_mul_f32_e32 v29, 0x44800000, v101
	v_med3_f32 v28, v28, s82, v13
	v_med3_f32 v29, v29, s82, v13
	v_mov_b32_e32 v93, 0
	v_cvt_pk_fp8_f32 v93, v28, v29
	v_mul_f32_e32 v87, 0x44800000, v103
	v_mul_f32_e32 v28, 0x44800000, v105
	v_med3_f32 v29, v87, s82, v13
	v_med3_f32 v28, v28, s82, v13
	v_cvt_pk_fp8_f32 v93, v29, v28 op_sel:[0,0,1]
	v_mul_f32_e32 v28, 0x44800000, v107
	v_mul_f32_e32 v29, 0x44800000, v109
	v_med3_f32 v28, v28, s82, v13
	v_med3_f32 v29, v29, s82, v13
	v_mov_b32_e32 v94, 0
	v_cvt_pk_fp8_f32 v94, v28, v29
	v_mul_f32_e32 v87, 0x44800000, v111
	v_mul_f32_e32 v28, 0x44800000, v113
	v_med3_f32 v29, v87, s82, v13
	v_med3_f32 v28, v28, s82, v13
	v_cvt_pk_fp8_f32 v94, v29, v28 op_sel:[0,0,1]
	v_mul_f32_e32 v28, 0x44800000, v115
	v_mul_f32_e32 v29, 0x44800000, v117
	v_med3_f32 v28, v28, s82, v13
	v_med3_f32 v29, v29, s82, v13
	v_mov_b32_e32 v95, 0
	v_cvt_pk_fp8_f32 v95, v28, v29
	v_mul_f32_e32 v87, 0x44800000, v119
	v_mul_f32_e32 v28, 0x44800000, v121
	v_med3_f32 v29, v87, s82, v13
	v_med3_f32 v28, v28, s82, v13
	v_cvt_pk_fp8_f32 v95, v29, v28 op_sel:[0,0,1]
	v_mad_u64_u32 v[124:125], s[48:49], s74, v10, v[122:123]
	v_mad_u64_u32 v[28:29], s[48:49], s74, v12, v[122:123]
	global_store_dwordx4 v[124:125], v[88:91], off nt
	global_store_dwordx4 v[28:29], v[92:95], off nt
	s_cbranch_execnz .LBB0_1534
	s_branch .LBB0_1533

; __device__ __forceinline__ unsigned cvt_pk_bf16(float lo, float hi) { unsigned r; asm volatile("v_cvt_pk_bf16_f32 %0, %1, %2" : "=v"(r) : "v"(lo), "v"(hi)); return r; }
; #define LAS __attribute__((address_space(3)))
; __device__ __forceinline__ void tr_range(const Params& p, LAS unsigned char* lds, int first, int stride, int end, int lane, int wave) {
;     ...
;         const int c = lane & 7;
; #pragma unroll
;         for (int j = 0; j < 8; ++j) { const int n = (lane >> 3) + 8 * j; const LAS float* s = scr + (8 * c) * 65 + n;
;             u32x4 o; o.x = pg8::cvt_pk_bf16(s[0 * 65], s[1 * 65]); o.y = pg8::cvt_pk_bf16(s[2 * 65], s[3 * 65]); o.z = pg8::cvt_pk_bf16(s[4 * 65], s[5 * 65]); o.w = pg8::cvt_pk_bf16(s[6 * 65], s[7 * 65]);
;             *(u32x4*)(cur.dst + (size_t)n * cur.K + 8 * c) = o; }
.LBB0_2009:
	ds_read2_b32 v[88:89], v11 offset1:65
	s_waitcnt lgkmcnt(0)
	v_cvt_pk_bf16_f32 v88, v88, v89
	ds_read2_b32 v[90:91], v11 offset0:130 offset1:195
	v_add_u32_e32 v87, 0x400, v11
	s_waitcnt lgkmcnt(0)
	v_cvt_pk_bf16_f32 v89, v90, v91
	ds_read2_b32 v[90:91], v87 offset0:4 offset1:69
	s_waitcnt lgkmcnt(0)
	v_cvt_pk_bf16_f32 v90, v90, v91
	ds_read2_b32 v[92:93], v87 offset0:134 offset1:199
	v_lshl_add_u64 v[28:29], s[2:3], 0, v[4:5]
	s_waitcnt lgkmcnt(0)
	v_cvt_pk_bf16_f32 v91, v92, v93
	v_mad_u64_u32 v[92:93], s[2:3], s68, v6, 0
	v_lshl_add_u64 v[92:93], v[92:93], 1, v[28:29]
	global_store_dwordx4 v[92:93], v[88:91], off nt
	ds_read2_b32 v[88:89], v11 offset0:8 offset1:73
	s_waitcnt lgkmcnt(0)
	v_cvt_pk_bf16_f32 v88, v88, v89
	ds_read2_b32 v[90:91], v11 offset0:138 offset1:203
	s_waitcnt lgkmcnt(0)
	v_cvt_pk_bf16_f32 v89, v90, v91
	ds_read2_b32 v[90:91], v87 offset0:12 offset1:77
	s_waitcnt lgkmcnt(0)
	v_cvt_pk_bf16_f32 v90, v90, v91
	ds_read2_b32 v[92:93], v87 offset0:142 offset1:207
	s_waitcnt lgkmcnt(0)
	v_cvt_pk_bf16_f32 v91, v92, v93
	v_mad_u64_u32 v[92:93], s[2:3], s68, v14, 0
	v_lshl_add_u64 v[92:93], v[92:93], 1, v[28:29]
	global_store_dwordx4 v[92:93], v[88:91], off nt
	ds_read2_b32 v[88:89], v11 offset0:16 offset1:81
	s_waitcnt lgkmcnt(0)
	v_cvt_pk_bf16_f32 v88, v88, v89
	ds_read2_b32 v[90:91], v11 offset0:146 offset1:211
	s_waitcnt lgkmcnt(0)
	v_cvt_pk_bf16_f32 v89, v90, v91
	ds_read2_b32 v[90:91], v87 offset0:20 offset1:85
	s_waitcnt lgkmcnt(0)
	v_cvt_pk_bf16_f32 v90, v90, v91
	ds_read2_b32 v[92:93], v87 offset0:150 offset1:215
	s_waitcnt lgkmcnt(0)
	v_cvt_pk_bf16_f32 v91, v92, v93
	v_mad_u64_u32 v[92:93], s[2:3], s68, v16, 0
	v_lshl_add_u64 v[92:93], v[92:93], 1, v[28:29]
	global_store_dwordx4 v[92:93], v[88:91], off nt
	ds_read2_b32 v[88:89], v11 offset0:24 offset1:89
	s_waitcnt lgkmcnt(0)
	v_cvt_pk_bf16_f32 v88, v88, v89
	ds_read2_b32 v[90:91], v11 offset0:154 offset1:219
	s_waitcnt lgkmcnt(0)
	v_cvt_pk_bf16_f32 v89, v90, v91
	ds_read2_b32 v[90:91], v87 offset0:28 offset1:93
	s_waitcnt lgkmcnt(0)
	v_cvt_pk_bf16_f32 v90, v90, v91
	ds_read2_b32 v[92:93], v87 offset0:158 offset1:223
	s_waitcnt lgkmcnt(0)
	v_cvt_pk_bf16_f32 v91, v92, v93
	v_mad_u64_u32 v[92:93], s[2:3], s68, v18, 0
	v_lshl_add_u64 v[92:93], v[92:93], 1, v[28:29]
	global_store_dwordx4 v[92:93], v[88:91], off nt
	ds_read2_b32 v[88:89], v11 offset0:32 offset1:97
	s_waitcnt lgkmcnt(0)
	v_cvt_pk_bf16_f32 v88, v88, v89
	ds_read2_b32 v[90:91], v11 offset0:162 offset1:227
	s_waitcnt lgkmcnt(0)
	v_cvt_pk_bf16_f32 v89, v90, v91
	ds_read2_b32 v[90:91], v87 offset0:36 offset1:101
	s_waitcnt lgkmcnt(0)
	v_cvt_pk_bf16_f32 v90, v90, v91
	ds_read2_b32 v[92:93], v87 offset0:166 offset1:231
	s_waitcnt lgkmcnt(0)
	v_cvt_pk_bf16_f32 v91, v92, v93
	v_mad_u64_u32 v[92:93], s[2:3], s68, v20, 0
	v_lshl_add_u64 v[92:93], v[92:93], 1, v[28:29]
	global_store_dwordx4 v[92:93], v[88:91], off nt
	ds_read2_b32 v[88:89], v11 offset0:40 offset1:105
	s_waitcnt lgkmcnt(0)
	v_cvt_pk_bf16_f32 v88, v88, v89
	ds_read2_b32 v[90:91], v11 offset0:170 offset1:235
	s_waitcnt lgkmcnt(0)
	v_cvt_pk_bf16_f32 v89, v90, v91
	ds_read2_b32 v[90:91], v87 offset0:44 offset1:109
	s_waitcnt lgkmcnt(0)
	v_cvt_pk_bf16_f32 v90, v90, v91
	ds_read2_b32 v[92:93], v87 offset0:174 offset1:239
	s_waitcnt lgkmcnt(0)
	v_cvt_pk_bf16_f32 v91, v92, v93
	v_mad_u64_u32 v[92:93], s[2:3], s68, v22, 0
	v_lshl_add_u64 v[92:93], v[92:93], 1, v[28:29]
	global_store_dwordx4 v[92:93], v[88:91], off nt
	ds_read2_b32 v[88:89], v11 offset0:48 offset1:113
	s_waitcnt lgkmcnt(0)
	v_cvt_pk_bf16_f32 v88, v88, v89
	ds_read2_b32 v[90:91], v11 offset0:178 offset1:243
	s_waitcnt lgkmcnt(0)
	v_cvt_pk_bf16_f32 v89, v90, v91
	ds_read2_b32 v[90:91], v87 offset0:52 offset1:117
	s_waitcnt lgkmcnt(0)
	v_cvt_pk_bf16_f32 v90, v90, v91
	ds_read2_b32 v[92:93], v87 offset0:182 offset1:247
	s_waitcnt lgkmcnt(0)
	v_cvt_pk_bf16_f32 v91, v92, v93
	v_mad_u64_u32 v[92:93], s[2:3], s68, v24, 0
	v_lshl_add_u64 v[92:93], v[92:93], 1, v[28:29]
	global_store_dwordx4 v[92:93], v[88:91], off nt
	ds_read2_b32 v[88:89], v11 offset0:56 offset1:121
	s_waitcnt lgkmcnt(0)
	v_cvt_pk_bf16_f32 v88, v88, v89
	ds_read2_b32 v[90:91], v11 offset0:186 offset1:251
	s_waitcnt lgkmcnt(0)
	v_cvt_pk_bf16_f32 v89, v90, v91
	ds_read2_b32 v[90:91], v87 offset0:60 offset1:125
	s_waitcnt lgkmcnt(0)
	v_cvt_pk_bf16_f32 v90, v90, v91
	ds_read2_b32 v[92:93], v87 offset0:190 offset1:255
	s_waitcnt lgkmcnt(0)
	v_cvt_pk_bf16_f32 v91, v92, v93
	v_mad_u64_u32 v[92:93], s[2:3], s68, v26, 0
	v_lshl_add_u64 v[28:29], v[92:93], 1, v[28:29]
	global_store_dwordx4 v[28:29], v[88:91], off nt

; #define LAS __attribute__((address_space(3)))
; __device__ __forceinline__ void tr_range(const Params& p, LAS unsigned char* lds, int first, int stride, int end, int lane, int wave) {
;     ...
;         if (cur.fp8) {
;             const int c = lane & 3;
; #pragma unroll
;             for (int j = 0; j < 4; ++j) { const int n = (lane >> 2) + 16 * j; const LAS float* s = scr + (16 * c) * 65 + n;
;                 u32x4 o;
;                 o.x = pk4_fp8(s[0 * 65] * W8_SCALE, s[1 * 65] * W8_SCALE, s[2 * 65] * W8_SCALE, s[3 * 65] * W8_SCALE);
;                 o.y = pk4_fp8(s[4 * 65] * W8_SCALE, s[5 * 65] * W8_SCALE, s[6 * 65] * W8_SCALE, s[7 * 65] * W8_SCALE);
;                 o.z = pk4_fp8(s[8 * 65] * W8_SCALE, s[9 * 65] * W8_SCALE, s[10 * 65] * W8_SCALE, s[11 * 65] * W8_SCALE);
;                 o.w = pk4_fp8(s[12 * 65] * W8_SCALE, s[13 * 65] * W8_SCALE, s[14 * 65] * W8_SCALE, s[15 * 65] * W8_SCALE);
;                 *(u32x4*)((unsigned char*)cur.dst + (size_t)n * cur.K + 16 * c) = o; }
.LBB0_2074:
	s_waitcnt lgkmcnt(0)
	s_cmp_eq_u32 s69, 0
	s_cbranch_scc1 .LBB0_2076
	ds_read2_b32 v[28:29], v9 offset1:16
	ds_read2_b32 v[92:93], v9 offset0:65 offset1:81
	ds_read2_b32 v[94:95], v9 offset0:130 offset1:146
	ds_read2_b32 v[96:97], v9 offset0:195 offset1:211
	v_mov_b32_e32 v88, 0
	s_waitcnt lgkmcnt(3)
	v_mul_f32_e32 v28, 0x44800000, v28
	s_waitcnt lgkmcnt(2)
	v_mul_f32_e32 v87, 0x44800000, v92
	v_med3_f32 v28, v28, s74, v13
	v_med3_f32 v87, v87, s74, v13
	v_cvt_pk_fp8_f32 v88, v28, v87
	v_add_u32_e32 v126, 0x400, v9
	ds_read2_b32 v[98:99], v126 offset0:4 offset1:20
	ds_read2_b32 v[100:101], v126 offset0:69 offset1:85
	ds_read2_b32 v[102:103], v126 offset0:134 offset1:150
	ds_read2_b32 v[104:105], v126 offset0:199 offset1:215
	s_waitcnt lgkmcnt(5)
	v_mul_f32_e32 v89, 0x44800000, v94
	s_waitcnt lgkmcnt(4)
	v_mul_f32_e32 v90, 0x44800000, v96
	v_med3_f32 v28, v89, s74, v13
	v_med3_f32 v87, v90, s74, v13
	v_cvt_pk_fp8_f32 v88, v28, v87 op_sel:[0,0,1]
	s_waitcnt lgkmcnt(3)
	v_mul_f32_e32 v28, 0x44800000, v98
	s_waitcnt lgkmcnt(2)
	v_mul_f32_e32 v87, 0x44800000, v100
	v_med3_f32 v28, v28, s74, v13
	v_med3_f32 v87, v87, s74, v13
	v_mov_b32_e32 v89, 0
	v_cvt_pk_fp8_f32 v89, v28, v87
	v_add_u32_e32 v127, 0x800, v9
	ds_read2_b32 v[106:107], v127 offset0:8 offset1:24
	ds_read2_b32 v[108:109], v127 offset0:73 offset1:89
	ds_read2_b32 v[110:111], v127 offset0:138 offset1:154
	ds_read2_b32 v[112:113], v127 offset0:203 offset1:219
	s_waitcnt lgkmcnt(5)
	v_mul_f32_e32 v90, 0x44800000, v102
	s_waitcnt lgkmcnt(4)
	v_mul_f32_e32 v91, 0x44800000, v104
	v_med3_f32 v28, v90, s74, v13
	v_med3_f32 v87, v91, s74, v13
	v_cvt_pk_fp8_f32 v89, v28, v87 op_sel:[0,0,1]
	s_waitcnt lgkmcnt(3)
	v_mul_f32_e32 v28, 0x44800000, v106
	s_waitcnt lgkmcnt(2)
	v_mul_f32_e32 v87, 0x44800000, v108
	v_med3_f32 v28, v28, s74, v13
	v_med3_f32 v87, v87, s74, v13
	v_mov_b32_e32 v90, 0
	v_cvt_pk_fp8_f32 v90, v28, v87
	v_add_u32_e32 v87, 0xc00, v9
	ds_read2_b32 v[114:115], v87 offset0:12 offset1:28
	ds_read2_b32 v[116:117], v87 offset0:77 offset1:93
	ds_read2_b32 v[118:119], v87 offset0:142 offset1:158
	s_waitcnt lgkmcnt(4)
	v_mul_f32_e32 v91, 0x44800000, v110
	s_waitcnt lgkmcnt(3)
	v_mul_f32_e32 v92, 0x44800000, v112
	v_med3_f32 v28, v91, s74, v13
	v_med3_f32 v91, v92, s74, v13
	ds_read2_b32 v[120:121], v87 offset0:207 offset1:223
	v_cvt_pk_fp8_f32 v90, v28, v91 op_sel:[0,0,1]
	s_waitcnt lgkmcnt(3)
	v_mul_f32_e32 v28, 0x44800000, v114
	s_waitcnt lgkmcnt(2)
	v_mul_f32_e32 v91, 0x44800000, v116
	v_med3_f32 v28, v28, s74, v13
	v_med3_f32 v94, v91, s74, v13
	v_mov_b32_e32 v91, 0
	v_cvt_pk_fp8_f32 v91, v28, v94
	s_waitcnt lgkmcnt(1)
	v_mul_f32_e32 v92, 0x44800000, v118
	s_waitcnt lgkmcnt(0)
	v_mul_f32_e32 v28, 0x44800000, v120
	v_med3_f32 v92, v92, s74, v13
	v_med3_f32 v28, v28, s74, v13
	v_cvt_pk_fp8_f32 v91, v92, v28 op_sel:[0,0,1]
	v_lshl_add_u64 v[122:123], s[2:3], 0, v[146:147]
	v_mad_u64_u32 v[124:125], s[46:47], s68, v2, v[122:123]
	v_mul_f32_e32 v28, 0x44800000, v29
	v_mul_f32_e32 v29, 0x44800000, v93
	global_store_dwordx4 v[124:125], v[88:91], off nt
	v_med3_f32 v28, v28, s74, v13
	v_med3_f32 v29, v29, s74, v13
	v_mov_b32_e32 v88, 0
	v_cvt_pk_fp8_f32 v88, v28, v29
	v_mul_f32_e32 v89, 0x44800000, v95
	v_mul_f32_e32 v28, 0x44800000, v97
	v_med3_f32 v29, v89, s74, v13
	v_med3_f32 v28, v28, s74, v13
	v_cvt_pk_fp8_f32 v88, v29, v28 op_sel:[0,0,1]
	v_mul_f32_e32 v28, 0x44800000, v99
	v_mul_f32_e32 v29, 0x44800000, v101
	v_med3_f32 v28, v28, s74, v13
	v_med3_f32 v29, v29, s74, v13
	v_mov_b32_e32 v89, 0
	v_cvt_pk_fp8_f32 v89, v28, v29
	v_mul_f32_e32 v90, 0x44800000, v103
	v_mul_f32_e32 v28, 0x44800000, v105
	v_med3_f32 v29, v90, s74, v13
	v_med3_f32 v28, v28, s74, v13
	v_cvt_pk_fp8_f32 v89, v29, v28 op_sel:[0,0,1]
	v_mul_f32_e32 v28, 0x44800000, v107
	v_mul_f32_e32 v29, 0x44800000, v109
	v_med3_f32 v28, v28, s74, v13
	v_med3_f32 v29, v29, s74, v13
	v_mov_b32_e32 v90, 0
	v_cvt_pk_fp8_f32 v90, v28, v29
	v_mul_f32_e32 v91, 0x44800000, v111
	v_mul_f32_e32 v28, 0x44800000, v113
	v_med3_f32 v29, v91, s74, v13
	v_med3_f32 v28, v28, s74, v13
	v_cvt_pk_fp8_f32 v90, v29, v28 op_sel:[0,0,1]
	v_mul_f32_e32 v28, 0x44800000, v115
	v_mul_f32_e32 v29, 0x44800000, v117
	v_med3_f32 v28, v28, s74, v13
	v_med3_f32 v29, v29, s74, v13
	v_mov_b32_e32 v91, 0
	v_cvt_pk_fp8_f32 v91, v28, v29
	v_mul_f32_e32 v92, 0x44800000, v119
	v_mul_f32_e32 v28, 0x44800000, v121
	v_med3_f32 v29, v92, s74, v13
	v_med3_f32 v28, v28, s74, v13
	v_cvt_pk_fp8_f32 v91, v29, v28 op_sel:[0,0,1]
	ds_read2_b32 v[92:93], v9 offset0:32 offset1:48
	ds_read2_b32 v[94:95], v9 offset0:97 offset1:113
	ds_read2_b32 v[96:97], v9 offset0:162 offset1:178
	ds_read2_b32 v[98:99], v9 offset0:227 offset1:243
	v_mad_u64_u32 v[28:29], s[46:47], s68, v8, v[122:123]
	global_store_dwordx4 v[28:29], v[88:91], off nt
	s_waitcnt lgkmcnt(3)
; #define LAS __attribute__((address_space(3)))
; __device__ __forceinline__ void tr_range(const Params& p, LAS unsigned char* lds, int first, int stride, int end, int lane, int wave) {
;     ...
;             for (int j = 0; j < 4; ++j) { const int n = (lane >> 2) + 16 * j; const LAS float* s = scr + (16 * c) * 65 + n;
;                 u32x4 o;
;                 o.x = pk4_fp8(s[0 * 65] * W8_SCALE, s[1 * 65] * W8_SCALE, s[2 * 65] * W8_SCALE, s[3 * 65] * W8_SCALE);
;                 o.y = pk4_fp8(s[4 * 65] * W8_SCALE, s[5 * 65] * W8_SCALE, s[6 * 65] * W8_SCALE, s[7 * 65] * W8_SCALE);
;                 o.z = pk4_fp8(s[8 * 65] * W8_SCALE, s[9 * 65] * W8_SCALE, s[10 * 65] * W8_SCALE, s[11 * 65] * W8_SCALE);
;                 o.w = pk4_fp8(s[12 * 65] * W8_SCALE, s[13 * 65] * W8_SCALE, s[14 * 65] * W8_SCALE, s[15 * 65] * W8_SCALE);
;                 *(u32x4*)((unsigned char*)cur.dst + (size_t)n * cur.K + 16 * c) = o; }
	v_mul_f32_e32 v28, 0x44800000, v92
	s_waitcnt lgkmcnt(2)
	v_mul_f32_e32 v29, 0x44800000, v94
	v_med3_f32 v28, v28, s74, v13
	v_med3_f32 v29, v29, s74, v13
	v_mov_b32_e32 v88, 0
	v_cvt_pk_fp8_f32 v88, v28, v29
	ds_read2_b32 v[28:29], v126 offset0:36 offset1:52
	ds_read2_b32 v[100:101], v126 offset0:101 offset1:117
	ds_read2_b32 v[102:103], v126 offset0:166 offset1:182
	ds_read2_b32 v[104:105], v126 offset0:231 offset1:247
	s_waitcnt lgkmcnt(5)
	v_mul_f32_e32 v89, 0x44800000, v96
	s_waitcnt lgkmcnt(4)
	v_mul_f32_e32 v90, 0x44800000, v98
	v_med3_f32 v89, v89, s74, v13
	v_med3_f32 v90, v90, s74, v13
	v_cvt_pk_fp8_f32 v88, v89, v90 op_sel:[0,0,1]
	s_waitcnt lgkmcnt(3)
	v_mul_f32_e32 v28, 0x44800000, v28
	s_waitcnt lgkmcnt(2)
	v_mul_f32_e32 v89, 0x44800000, v100
	v_med3_f32 v28, v28, s74, v13
	v_med3_f32 v92, v89, s74, v13
	v_mov_b32_e32 v89, 0
	v_cvt_pk_fp8_f32 v89, v28, v92
	ds_read2_b32 v[106:107], v127 offset0:40 offset1:56
	ds_read2_b32 v[108:109], v127 offset0:105 offset1:121
	ds_read2_b32 v[110:111], v127 offset0:170 offset1:186
	ds_read2_b32 v[112:113], v127 offset0:235 offset1:251
	s_waitcnt lgkmcnt(5)
	v_mul_f32_e32 v90, 0x44800000, v102
	s_waitcnt lgkmcnt(4)
	v_mul_f32_e32 v91, 0x44800000, v104
	v_med3_f32 v28, v90, s74, v13
	v_med3_f32 v90, v91, s74, v13
	v_cvt_pk_fp8_f32 v89, v28, v90 op_sel:[0,0,1]
	s_waitcnt lgkmcnt(3)
	v_mul_f32_e32 v28, 0x44800000, v106
	s_waitcnt lgkmcnt(2)
	v_mul_f32_e32 v90, 0x44800000, v108
	v_med3_f32 v28, v28, s74, v13
	v_med3_f32 v94, v90, s74, v13
	v_mov_b32_e32 v90, 0
	v_cvt_pk_fp8_f32 v90, v28, v94
	ds_read2_b32 v[114:115], v87 offset0:44 offset1:60
	ds_read2_b32 v[116:117], v87 offset0:109 offset1:125
	ds_read2_b32 v[118:119], v87 offset0:174 offset1:190
	s_waitcnt lgkmcnt(4)
	v_mul_f32_e32 v91, 0x44800000, v110
	s_waitcnt lgkmcnt(3)
	v_mul_f32_e32 v92, 0x44800000, v112
	v_med3_f32 v28, v91, s74, v13
	v_med3_f32 v91, v92, s74, v13
	ds_read2_b32 v[120:121], v87 offset0:239 offset1:255
	v_cvt_pk_fp8_f32 v90, v28, v91 op_sel:[0,0,1]
	s_waitcnt lgkmcnt(3)
	v_mul_f32_e32 v28, 0x44800000, v114
	s_waitcnt lgkmcnt(2)
	v_mul_f32_e32 v91, 0x44800000, v116
	v_med3_f32 v28, v28, s74, v13
	v_med3_f32 v87, v91, s74, v13
	v_mov_b32_e32 v91, 0
	v_cvt_pk_fp8_f32 v91, v28, v87
	s_waitcnt lgkmcnt(1)
	v_mul_f32_e32 v92, 0x44800000, v118
	s_waitcnt lgkmcnt(0)
	v_mul_f32_e32 v28, 0x44800000, v120
	v_med3_f32 v87, v92, s74, v13
	v_med3_f32 v28, v28, s74, v13
	v_cvt_pk_fp8_f32 v91, v87, v28 op_sel:[0,0,1]
	v_mul_f32_e32 v28, 0x44800000, v93
	v_mul_f32_e32 v87, 0x44800000, v95
	v_med3_f32 v28, v28, s74, v13
	v_med3_f32 v87, v87, s74, v13
	v_mov_b32_e32 v92, 0
	v_cvt_pk_fp8_f32 v92, v28, v87
	v_mul_f32_e32 v93, 0x44800000, v97
	v_mul_f32_e32 v28, 0x44800000, v99
	v_med3_f32 v87, v93, s74, v13
	v_med3_f32 v28, v28, s74, v13
	v_cvt_pk_fp8_f32 v92, v87, v28 op_sel:[0,0,1]
	v_mul_f32_e32 v28, 0x44800000, v29
	v_mul_f32_e32 v29, 0x44800000, v101
	v_med3_f32 v28, v28, s74, v13
	v_med3_f32 v29, v29, s74, v13
	v_mov_b32_e32 v93, 0
	v_cvt_pk_fp8_f32 v93, v28, v29
	v_mul_f32_e32 v87, 0x44800000, v103
	v_mul_f32_e32 v28, 0x44800000, v105
	v_med3_f32 v29, v87, s74, v13
	v_med3_f32 v28, v28, s74, v13
	v_cvt_pk_fp8_f32 v93, v29, v28 op_sel:[0,0,1]
	v_mul_f32_e32 v28, 0x44800000, v107
	v_mul_f32_e32 v29, 0x44800000, v109
	v_med3_f32 v28, v28, s74, v13
	v_med3_f32 v29, v29, s74, v13
	v_mov_b32_e32 v94, 0
	v_cvt_pk_fp8_f32 v94, v28, v29
	v_mul_f32_e32 v87, 0x44800000, v111
	v_mul_f32_e32 v28, 0x44800000, v113
	v_med3_f32 v29, v87, s74, v13
	v_med3_f32 v28, v28, s74, v13
	v_cvt_pk_fp8_f32 v94, v29, v28 op_sel:[0,0,1]
	v_mul_f32_e32 v28, 0x44800000, v115
	v_mul_f32_e32 v29, 0x44800000, v117
	v_med3_f32 v28, v28, s74, v13
	v_med3_f32 v29, v29, s74, v13
	v_mov_b32_e32 v95, 0
	v_cvt_pk_fp8_f32 v95, v28, v29
	v_mul_f32_e32 v87, 0x44800000, v119
	v_mul_f32_e32 v28, 0x44800000, v121
	v_med3_f32 v29, v87, s74, v13
	v_med3_f32 v28, v28, s74, v13
	v_cvt_pk_fp8_f32 v95, v29, v28 op_sel:[0,0,1]
	v_mad_u64_u32 v[124:125], s[46:47], s68, v10, v[122:123]
	v_mad_u64_u32 v[28:29], s[46:47], s68, v12, v[122:123]
	global_store_dwordx4 v[124:125], v[88:91], off nt
	global_store_dwordx4 v[28:29], v[92:95], off nt
	s_cbranch_execnz .LBB0_2010
	s_branch .LBB0_2009
